# next-tile prefetch: hybrid K-loop setup and first weight-tile DMA hoisted above accumulator zeroing, extra barrier dropped
# baseline (speedup 1.0000x reference)
; __device__ __forceinline__ int tid_opaque() { int t = threadIdx.x; asm volatile("" : "+v"(t)); return t; }
; template <int MI, int NI>
; __device__ __forceinline__ void gemm_kloop(const bf16* __restrict__ A, size_t lda, const bf16* __restrict__ Bt, size_t ldb, int K,
;                                            f16v (&acc)[MI][NI], bf16* sA, bf16* sB) {
;   const int tid = tid_opaque(), lane = tid & 63, w = tid >> 6;
;   const int r = lane & 31, hh = lane >> 5;
;   const int wm = w >> 1, wn = w & 1;
;   const int lrow = tid >> 3, lseg = tid & 7;
;   u4v ra[2 * MI], rb[2 * NI];
;   const int KT = K >> 6;
; #pragma unroll
;   for (int i = 0; i < 2 * MI; ++i) ra[i] = *(const u4v*)(A + (size_t)(lrow + 32 * i) * lda + lseg * 8);
; #pragma unroll
;   for (int i = 0; i < 2 * NI; ++i) rb[i] = *(const u4v*)(Bt + (size_t)(lrow + 32 * i) * ldb + lseg * 8);
;   unsigned pfs = 0;
;   {
;     if (tid < 64 * MI) pfs ^= *(const unsigned*)(A + (size_t)tid * lda + 64) ^ *(const unsigned*)(A + (size_t)tid * lda + 128);
;     if (tid < 64 * NI) pfs ^= *(const unsigned*)(Bt + (size_t)tid * ldb + 64) ^ *(const unsigned*)(Bt + (size_t)tid * ldb + 128);
;   }
;   for (int kt = 0; kt < KT; ++kt) {
; __device__ __forceinline__ void run_phase(const Params& p, int ph, char* smem, int* s_item, int dup, int dryflag) {
;     ...
;       for (int sq = bloc; sq < 16 * 8; sq += nloc) { int mt, nt; decode_tile(sq, 8, 16, 4, xcd, mt, nt); resid_tile(p, p.act, 2816, p.WfdT, 2816, mt, nt, false, sA, sB, dry); }
.LBB0_16:
	s_lshr_b32 s2, s0, 3
	s_and_b32 s24, s2, 12
	s_lshl_b32 s2, s24, 3
	s_sub_i32 s2, s0, s2
	s_bfe_i32 s3, s2, 0x80000
	s_bfe_u32 s3, s3, 0x2000d
	s_add_i32 s3, s2, s3
	s_bfe_i32 s21, s3, 0x80000
	s_and_b32 s3, s3, 0xfc
	s_sub_i32 s2, s2, s3
	s_or_b32 s20, s24, s88
	s_sext_i32_i8 s25, s2
	s_add_i32 s20, s20, s25
	s_mul_i32 s2, s20, 0xb0000
	s_sext_i32_i16 s21, s21
	s_ashr_i32 s3, s2, 31
	s_ashr_i32 s21, s21, 2
	s_lshl_b64 s[2:3], s[2:3], 1
	v_readlane_b32 s28, v254, 12
	v_mov_b32_e32 v8, v195
	v_readlane_b32 s29, v254, 13
	s_add_u32 s2, s28, s2
	s_addc_u32 s3, s29, s3
	v_lshlrev_b32_e32 v0, 4, v8
	v_ashrrev_i32_e32 v9, 3, v8
	v_and_b32_e32 v0, 0x70, v0
	v_lshl_add_u64 v[2:3], s[2:3], 0, v[0:1]
	s_movk_i32 s26, 0x1600
	v_add_u32_e32 v10, 32, v9
	v_mad_i64_i32 v[4:5], s[2:3], v9, s26, v[2:3]
	v_mad_i64_i32 v[6:7], s[2:3], v10, s26, v[2:3]
	v_add_u32_e32 v11, 64, v9
	v_add_u32_e32 v12, 0x60, v9
	s_mul_i32 s22, s21, 0x58000
	global_load_dwordx4 v[134:137], v[4:5], off
	global_load_dwordx4 v[138:141], v[6:7], off
	v_mad_i64_i32 v[4:5], s[2:3], v11, s26, v[2:3]
	v_mad_i64_i32 v[6:7], s[2:3], v12, s26, v[2:3]
	s_ashr_i32 s23, s22, 31
	global_load_dwordx4 v[142:145], v[4:5], off
	global_load_dwordx4 v[146:149], v[6:7], off
	v_add_u32_e32 v4, 0x80, v9
	v_add_u32_e32 v6, 0xa0, v9
	s_lshl_b64 s[22:23], s[22:23], 1
	v_readlane_b32 s64, v252, 23
	v_mad_i64_i32 v[4:5], s[2:3], v4, s26, v[2:3]
	v_mad_i64_i32 v[6:7], s[2:3], v6, s26, v[2:3]
	v_readlane_b32 s65, v252, 24
	s_add_u32 s22, s64, s22
	global_load_dwordx4 v[154:157], v[4:5], off
	global_load_dwordx4 v[150:153], v[6:7], off
	v_add_u32_e32 v4, 0xc0, v9
	v_add_u32_e32 v6, 0xe0, v9
	s_addc_u32 s23, s65, s23
	v_mad_i64_i32 v[4:5], s[2:3], v4, s26, v[2:3]
	v_mad_i64_i32 v[2:3], s[2:3], v6, s26, v[2:3]
	global_load_dwordx4 v[162:165], v[4:5], off
	global_load_dwordx4 v[158:161], v[2:3], off
	v_lshl_add_u64 v[2:3], s[22:23], 0, v[0:1]
	v_mad_i64_i32 v[4:5], s[2:3], v9, s26, v[2:3]
	v_mad_i64_i32 v[6:7], s[2:3], v10, s26, v[2:3]
	v_mad_i64_i32 v[4:5], s[2:3], v11, s26, v[2:3]
	v_mad_i64_i32 v[2:3], s[2:3], v12, s26, v[2:3]
	v_and_b32_e32 v2, 0xfffff9f, v8
	v_lshrrev_b32_e32 v3, 1, v8
	v_and_b32_e32 v4, 16, v3
	v_and_b32_e32 v3, 0x5f, v8
	v_mul_lo_u32 v6, v2, s33
	v_or_b32_e32 v2, 0x60, v8
	v_mul_lo_u32 v7, v2, s33
	v_mul_u32_u24_e32 v8, 0x90, v3
	v_mad_i64_i32 v[2:3], s[2:3], v9, s26, 0
	s_add_i32 s2, s88, s24
	s_add_i32 s2, s2, s25
	s_mul_i32 s2, s2, 0xb0000
	s_ashr_i32 s3, s2, 31
	s_lshl_b64 s[2:3], s[2:3], 1
	s_add_u32 s2, s28, s2
	v_or_b32_e32 v2, v2, v0
	s_addc_u32 s3, s29, s3
	v_mul_lo_u32 v5, v9, s33
	s_waitcnt vmcnt(31)
	v_lshl_add_u64 v[178:179], s[2:3], 0, v[2:3]
	v_lshl_add_u64 v[180:181], s[22:23], 0, v[2:3]
	v_mov_b32_e32 v2, 0
	s_mov_b64 s[2:3], 0
	s_waitcnt vmcnt(30)
	v_add_u32_e32 v184, v0, v5
	v_add_u32_e32 v182, v4, v6
	v_add_u32_e32 v0, v4, v7
	v_add_u32_e32 v183, v4, v8
	v_readfirstlane_b32 s56, v178
	v_readfirstlane_b32 s57, v179
	v_readfirstlane_b32 s58, v180
	v_readfirstlane_b32 s59, v181
	v_readfirstlane_b32 s94, v195
	v_subrev_u32_e32 v178, s56, v178
	v_add_u32_e32 v179, 0x2c000, v178
	v_add_u32_e32 v180, 0x58000, v178
	v_add_u32_e32 v181, 0x84000, v178
	v_add_u32_e32 v185, 0xb0000, v178
	v_add_u32_e32 v222, 0xdc000, v178
	v_add_u32_e32 v223, 0x108000, v178
	v_add_u32_e32 v227, 0x134000, v178
	s_lshr_b32 s94, s94, 6
	s_mul_i32 s95, s94, 0xb000
	s_sub_u32 s58, s58, s95
	s_subb_u32 s59, s59, 0
	s_lshl_b32 s96, s94, 12
	s_add_u32 s96, s96, 36864
	v_and_b32_e32 v170, 63, v195
	v_lshrrev_b32_e32 v171, 3, v170
	v_lshrrev_b32_e32 v172, 4, v170
	v_and_b32_e32 v173, 7, v170
	v_xor_b32_e32 v172, v172, v173
	v_lshlrev_b32_e32 v172, 4, v172
	v_lshrrev_b32_e32 v173, 6, v195
	v_lshl_add_u32 v170, v173, 5, v171
	v_mul_u32_u24_e32 v170, 0x1600, v170
	v_add_u32_e32 v130, v170, v172
	v_xor_b32_e32 v172, 64, v172
	v_add_u32_e32 v170, v170, v172
	v_add_u32_e32 v131, 0xac00, v170
	v_add_u32_e32 v132, 0x15800, v130
	v_add_u32_e32 v133, 0x20400, v170
	v_and_b32_e32 v170, 31, v195
	v_bfe_u32 v171, v195, 5, 1
	v_bfe_u32 v172, v170, 1, 3
	v_xor_b32_e32 v171, v171, v172
	v_lshlrev_b32_e32 v171, 4, v171
	v_bfe_u32 v172, v195, 6, 1
	v_lshl_add_u32 v172, v172, 6, v170
	v_lshl_add_u32 v166, v172, 7, v171
	v_xor_b32_e32 v167, 32, v166
	v_xor_b32_e32 v168, 64, v166
	v_xor_b32_e32 v169, 96, v166
	s_add_u32 m0, s96, 0
	s_nop 0
	global_load_lds_dwordx4 v130, s[58:59] offset:0
	global_load_lds_dwordx4 v131, s[58:59] offset:1024
	global_load_lds_dwordx4 v132, s[58:59] offset:2048
	global_load_lds_dwordx4 v133, s[58:59] offset:3072
	v_mov_b32_e32 v3, v2
	v_mov_b32_e32 v4, v2
	v_mov_b32_e32 v5, v2
	v_mov_b32_e32 v6, v2
	v_mov_b32_e32 v7, v2
	v_mov_b32_e32 v8, v2
	v_mov_b32_e32 v9, v2
	v_mov_b32_e32 v10, v2
	v_mov_b32_e32 v11, v2
	v_mov_b32_e32 v12, v2
	v_mov_b32_e32 v13, v2
	v_mov_b32_e32 v14, v2
	v_mov_b32_e32 v15, v2
	v_mov_b32_e32 v16, v2
	v_mov_b32_e32 v17, v2
	v_mov_b32_e32 v18, v2
	v_mov_b32_e32 v19, v2
	v_mov_b32_e32 v20, v2
	v_mov_b32_e32 v21, v2
	v_mov_b32_e32 v22, v2
	v_mov_b32_e32 v23, v2
	v_mov_b32_e32 v24, v2
	v_mov_b32_e32 v25, v2
	v_mov_b32_e32 v26, v2
	v_mov_b32_e32 v27, v2
	v_mov_b32_e32 v28, v2
	v_mov_b32_e32 v29, v2
	v_mov_b32_e32 v30, v2
	v_mov_b32_e32 v31, v2
	v_mov_b32_e32 v32, v2
	v_mov_b32_e32 v33, v2
	v_mov_b32_e32 v34, v2
	v_mov_b32_e32 v35, v2
	v_mov_b32_e32 v36, v2
	v_mov_b32_e32 v37, v2
	v_mov_b32_e32 v38, v2
	v_mov_b32_e32 v39, v2
	v_mov_b32_e32 v40, v2
	v_mov_b32_e32 v41, v2
	v_mov_b32_e32 v42, v2
	v_mov_b32_e32 v43, v2
	v_mov_b32_e32 v44, v2
	v_mov_b32_e32 v45, v2
	v_mov_b32_e32 v46, v2
	v_mov_b32_e32 v47, v2
	v_mov_b32_e32 v48, v2
	v_mov_b32_e32 v49, v2
	v_mov_b32_e32 v50, v2
; #define MFMA(a, b, c) __builtin_amdgcn_mfma_f32_32x32x16_bf16((a), (b), (c), 0, 0, 0)
; #define ZERO_ACC(acc, MI_, NI_)                 \
;   _Pragma("unroll") for (int mi = 0; mi < MI_; ++mi) \
;   _Pragma("unroll") for (int ni = 0; ni < NI_; ++ni) \
;   _Pragma("unroll") for (int e = 0; e < 16; ++e) acc[mi][ni][e] = 0.f;
; template <int MI, int NI>
; __device__ __forceinline__ void gemm_kloop(const bf16* __restrict__ A, size_t lda, const bf16* __restrict__ Bt, size_t ldb, int K,
;                                            f16v (&acc)[MI][NI], bf16* sA, bf16* sB) {
;     ...
;   for (int kt = 0; kt < KT; ++kt) {
;     __syncthreads();
; #pragma unroll
;     for (int i = 0; i < 2 * MI; ++i) *(u4v*)(sA + (lrow + 32 * i) * 72 + lseg * 8) = ra[i];
; #pragma unroll
;     for (int i = 0; i < 2 * NI; ++i) *(u4v*)(sB + (lrow + 32 * i) * 72 + lseg * 8) = rb[i];
;     __syncthreads();
;     if (kt + 3 < KT) {
;       const int k2 = (kt + 3) << 6;
;       if (tid < 64 * MI) pfs ^= *(const unsigned*)(A + (size_t)tid * lda + k2);
;       if (tid < 64 * NI) pfs ^= *(const unsigned*)(Bt + (size_t)tid * ldb + k2);
;     }
;     if (kt + 1 < KT) {
;       const int k0 = (kt + 1) << 6;
; #pragma unroll
;       for (int i = 0; i < 2 * MI; ++i) ra[i] = *(const u4v*)(A + (size_t)(lrow + 32 * i) * lda + k0 + lseg * 8);
; #pragma unroll
;       for (int i = 0; i < 2 * NI; ++i) rb[i] = *(const u4v*)(Bt + (size_t)(lrow + 32 * i) * ldb + k0 + lseg * 8);
;     }
; #pragma unroll
;     for (int ks = 0; ks < 4; ++ks) {
;       s8v a[MI], b[NI];
; #pragma unroll
;       for (int mi = 0; mi < MI; ++mi) a[mi] = *(const s8v*)(sA + (wm * 32 * MI + mi * 32 + r) * 72 + ks * 16 + hh * 8);
; #pragma unroll
;       for (int ni = 0; ni < NI; ++ni) b[ni] = *(const s8v*)(sB + (wn * 32 * NI + ni * 32 + r) * 72 + ks * 16 + hh * 8);
; #pragma unroll
;       for (int mi = 0; mi < MI; ++mi)
; #pragma unroll
;         for (int ni = 0; ni < NI; ++ni) acc[mi][ni] = MFMA(a[mi], b[ni], acc[mi][ni]);
; __device__ __forceinline__ void resid_tile(const Params& p, const bf16* A, size_t lda, const bf16* Bt, int K, int mt, int nt, bool x_from_input, bf16* sA, bf16* sB, int dry) {
;     ...
;   ZERO_ACC(acc, 4, 2)
	v_mov_b32_e32 v51, v2
	v_mov_b32_e32 v52, v2
	v_mov_b32_e32 v53, v2
	v_mov_b32_e32 v54, v2
	v_mov_b32_e32 v55, v2
	v_mov_b32_e32 v56, v2
	v_mov_b32_e32 v57, v2
	v_mov_b32_e32 v58, v2
	v_mov_b32_e32 v59, v2
	v_mov_b32_e32 v60, v2
	v_mov_b32_e32 v61, v2
	v_mov_b32_e32 v62, v2
	v_mov_b32_e32 v63, v2
	v_mov_b32_e32 v64, v2
	v_mov_b32_e32 v65, v2
	v_mov_b32_e32 v66, v2
	v_mov_b32_e32 v67, v2
	v_mov_b32_e32 v68, v2
	v_mov_b32_e32 v69, v2
	v_mov_b32_e32 v70, v2
	v_mov_b32_e32 v71, v2
	v_mov_b32_e32 v72, v2
	v_mov_b32_e32 v73, v2
	v_mov_b32_e32 v74, v2
	v_mov_b32_e32 v75, v2
	v_mov_b32_e32 v76, v2
	v_mov_b32_e32 v77, v2
	v_mov_b32_e32 v78, v2
	v_mov_b32_e32 v79, v2
	v_mov_b32_e32 v80, v2
	v_mov_b32_e32 v81, v2
	v_mov_b32_e32 v82, v2
	v_mov_b32_e32 v83, v2
	v_mov_b32_e32 v84, v2
	v_mov_b32_e32 v85, v2
	v_mov_b32_e32 v86, v2
	v_mov_b32_e32 v87, v2
	v_mov_b32_e32 v88, v2
	v_mov_b32_e32 v89, v2
	v_mov_b32_e32 v90, v2
	v_mov_b32_e32 v91, v2
	v_mov_b32_e32 v92, v2
	v_mov_b32_e32 v93, v2
	v_mov_b32_e32 v94, v2
	v_mov_b32_e32 v95, v2
	v_mov_b32_e32 v96, v2
	v_mov_b32_e32 v97, v2
	v_mov_b32_e32 v98, v2
	v_mov_b32_e32 v99, v2
	v_mov_b32_e32 v100, v2
	v_mov_b32_e32 v101, v2
	v_mov_b32_e32 v102, v2
	v_mov_b32_e32 v103, v2
	v_mov_b32_e32 v104, v2
	v_mov_b32_e32 v105, v2
	v_mov_b32_e32 v106, v2
	v_mov_b32_e32 v107, v2
	v_mov_b32_e32 v108, v2
	v_mov_b32_e32 v109, v2
	v_mov_b32_e32 v110, v2
	v_mov_b32_e32 v111, v2
	v_mov_b32_e32 v112, v2
	v_mov_b32_e32 v113, v2
	v_mov_b32_e32 v114, v2
	v_mov_b32_e32 v115, v2
	v_mov_b32_e32 v116, v2
	v_mov_b32_e32 v117, v2
	v_mov_b32_e32 v118, v2
	v_mov_b32_e32 v119, v2
	v_mov_b32_e32 v120, v2
	v_mov_b32_e32 v121, v2
	v_mov_b32_e32 v122, v2
	v_mov_b32_e32 v123, v2
	v_mov_b32_e32 v124, v2
	v_mov_b32_e32 v125, v2
	v_mov_b32_e32 v126, v2
	v_mov_b32_e32 v127, v2
	v_mov_b32_e32 v128, v2
	v_mov_b32_e32 v129, v2
	s_mov_b32 s23, 0x58000
	s_mov_b32 s24, 0x2c000
	s_mov_b32 s25, 0x84000
	v_readlane_b32 s30, v254, 14
	v_readlane_b32 s31, v254, 15
	v_readlane_b32 s66, v252, 25
	v_readlane_b32 s67, v252, 26
	v_readlane_b32 s68, v252, 27
	v_readlane_b32 s69, v252, 28
	v_readlane_b32 s70, v252, 29
	v_readlane_b32 s71, v252, 30
	v_readlane_b32 s72, v252, 31
	v_readlane_b32 s73, v252, 32
	v_readlane_b32 s74, v252, 33
	v_readlane_b32 s75, v252, 34
	v_readlane_b32 s76, v252, 35
	v_readlane_b32 s77, v252, 36
	v_readlane_b32 s78, v252, 37
	v_readlane_b32 s79, v252, 38
	s_barrier
	s_waitcnt vmcnt(11)
	ds_write_b128 v184, v[134:137]
	s_waitcnt vmcnt(10)
	ds_write_b128 v184, v[138:141] offset:4608
	s_waitcnt vmcnt(9)
	ds_write_b128 v184, v[142:145] offset:9216
	s_waitcnt vmcnt(8)
	ds_write_b128 v184, v[146:149] offset:13824
	s_waitcnt vmcnt(7)
	ds_write_b128 v184, v[154:157] offset:18432
	s_waitcnt vmcnt(6)
	ds_write_b128 v184, v[150:153] offset:23040
	s_waitcnt vmcnt(5)
	ds_write_b128 v184, v[162:165] offset:27648
	s_waitcnt vmcnt(4)
	ds_write_b128 v184, v[158:161] offset:32256
	s_waitcnt vmcnt(0) lgkmcnt(0)
	s_barrier
	ds_read_b128 v[186:189], v182
	ds_read_b128 v[204:207], v166 offset:36864
	ds_read_b128 v[208:211], v166 offset:40960
	ds_read_b128 v[190:193], v182 offset:4608
	ds_read_b128 v[196:199], v182 offset:9216
	ds_read_b128 v[200:203], v0
	ds_read_b128 v[212:215], v182 offset:32
	ds_read_b128 v[244:247], v167 offset:36864
	ds_read_b128 v[248:251], v167 offset:40960
	ds_read_b128 v[216:219], v182 offset:4640
	ds_read_b128 v[232:235], v182 offset:9248
	ds_read_b128 v[236:239], v0 offset:32
	s_waitcnt lgkmcnt(10)
	v_mfma_f32_32x32x16_bf16 v[114:129], v[186:189], v[204:207], v[114:129]
	s_add_u32 m0, s96, 16256
	s_nop 0
	s_waitcnt lgkmcnt(9)
	v_mfma_f32_32x32x16_bf16 v[98:113], v[186:189], v[208:211], v[98:113]
	global_load_lds_dwordx4 v130, s[58:59] offset:128
	ds_read_b128 v[186:189], v182 offset:64
	s_waitcnt lgkmcnt(9)
	v_mfma_f32_32x32x16_bf16 v[82:97], v[190:193], v[204:207], v[82:97]
	global_load_lds_dwordx4 v131, s[58:59] offset:1152
	v_mfma_f32_32x32x16_bf16 v[66:81], v[190:193], v[208:211], v[66:81]
	global_load_lds_dwordx4 v132, s[58:59] offset:2176
	ds_read_b128 v[190:193], v182 offset:4672
	s_waitcnt lgkmcnt(9)
	v_mfma_f32_32x32x16_bf16 v[50:65], v[196:199], v[204:207], v[50:65]
	global_load_lds_dwordx4 v133, s[58:59] offset:3200
	v_mfma_f32_32x32x16_bf16 v[34:49], v[196:199], v[208:211], v[34:49]
	global_load_dwordx4 v[134:137], v178, s[56:57] offset:128
	ds_read_b128 v[196:199], v182 offset:9280
	s_waitcnt lgkmcnt(9)
	v_mfma_f32_32x32x16_bf16 v[18:33], v[200:203], v[204:207], v[18:33]
	global_load_dwordx4 v[138:141], v179, s[56:57] offset:128
	v_mfma_f32_32x32x16_bf16 v[2:17], v[200:203], v[208:211], v[2:17]
	global_load_dwordx4 v[142:145], v180, s[56:57] offset:128
	ds_read_b128 v[200:203], v0 offset:64
	ds_read_b128 v[204:207], v168 offset:36864
	ds_read_b128 v[208:211], v168 offset:40960
	s_waitcnt lgkmcnt(10)
	v_mfma_f32_32x32x16_bf16 v[114:129], v[212:215], v[244:247], v[114:129]
	global_load_dwordx4 v[146:149], v181, s[56:57] offset:128
	s_waitcnt lgkmcnt(9)
	v_mfma_f32_32x32x16_bf16 v[98:113], v[212:215], v[248:251], v[98:113]
	global_load_dwordx4 v[154:157], v185, s[56:57] offset:128
	ds_read_b128 v[212:215], v182 offset:96
	s_waitcnt lgkmcnt(9)
	v_mfma_f32_32x32x16_bf16 v[82:97], v[216:219], v[244:247], v[82:97]
	global_load_dwordx4 v[150:153], v222, s[56:57] offset:128
	v_mfma_f32_32x32x16_bf16 v[66:81], v[216:219], v[248:251], v[66:81]
	global_load_dwordx4 v[162:165], v223, s[56:57] offset:128
	ds_read_b128 v[216:219], v182 offset:4704
	s_waitcnt lgkmcnt(9)
	v_mfma_f32_32x32x16_bf16 v[50:65], v[232:235], v[244:247], v[50:65]
	global_load_dwordx4 v[158:161], v227, s[56:57] offset:128
	v_mfma_f32_32x32x16_bf16 v[34:49], v[232:235], v[248:251], v[34:49]
	ds_read_b128 v[232:235], v182 offset:9312
	s_waitcnt lgkmcnt(9)
; #define MFMA(a, b, c) __builtin_amdgcn_mfma_f32_32x32x16_bf16((a), (b), (c), 0, 0, 0)
; template <int MI, int NI>
; __device__ __forceinline__ void gemm_kloop(const bf16* __restrict__ A, size_t lda, const bf16* __restrict__ Bt, size_t ldb, int K,
;                                            f16v (&acc)[MI][NI], bf16* sA, bf16* sB) {
;     ...
;   for (int kt = 0; kt < KT; ++kt) {
;     __syncthreads();
; #pragma unroll
;     for (int i = 0; i < 2 * MI; ++i) *(u4v*)(sA + (lrow + 32 * i) * 72 + lseg * 8) = ra[i];
; #pragma unroll
;     for (int i = 0; i < 2 * NI; ++i) *(u4v*)(sB + (lrow + 32 * i) * 72 + lseg * 8) = rb[i];
;     __syncthreads();
;     if (kt + 3 < KT) {
;       const int k2 = (kt + 3) << 6;
;       if (tid < 64 * MI) pfs ^= *(const unsigned*)(A + (size_t)tid * lda + k2);
;       if (tid < 64 * NI) pfs ^= *(const unsigned*)(Bt + (size_t)tid * ldb + k2);
;     }
;     if (kt + 1 < KT) {
;       const int k0 = (kt + 1) << 6;
; #pragma unroll
;       for (int i = 0; i < 2 * MI; ++i) ra[i] = *(const u4v*)(A + (size_t)(lrow + 32 * i) * lda + k0 + lseg * 8);
; #pragma unroll
;       for (int i = 0; i < 2 * NI; ++i) rb[i] = *(const u4v*)(Bt + (size_t)(lrow + 32 * i) * ldb + k0 + lseg * 8);
;     }
; #pragma unroll
;     for (int ks = 0; ks < 4; ++ks) {
;       s8v a[MI], b[NI];
; #pragma unroll
;       for (int mi = 0; mi < MI; ++mi) a[mi] = *(const s8v*)(sA + (wm * 32 * MI + mi * 32 + r) * 72 + ks * 16 + hh * 8);
; #pragma unroll
;       for (int ni = 0; ni < NI; ++ni) b[ni] = *(const s8v*)(sB + (wn * 32 * NI + ni * 32 + r) * 72 + ks * 16 + hh * 8);
; #pragma unroll
;       for (int mi = 0; mi < MI; ++mi)
; #pragma unroll
;         for (int ni = 0; ni < NI; ++ni) acc[mi][ni] = MFMA(a[mi], b[ni], acc[mi][ni]);
	v_mfma_f32_32x32x16_bf16 v[18:33], v[236:239], v[244:247], v[18:33]
	v_mfma_f32_32x32x16_bf16 v[2:17], v[236:239], v[248:251], v[2:17]
	ds_read_b128 v[236:239], v0 offset:96
	ds_read_b128 v[244:247], v169 offset:36864
	ds_read_b128 v[248:251], v169 offset:40960
	s_waitcnt lgkmcnt(7)
	v_mfma_f32_32x32x16_bf16 v[114:129], v[186:189], v[204:207], v[114:129]
	s_waitcnt lgkmcnt(6)
	v_mfma_f32_32x32x16_bf16 v[98:113], v[186:189], v[208:211], v[98:113]
	v_mfma_f32_32x32x16_bf16 v[82:97], v[190:193], v[204:207], v[82:97]
	v_mfma_f32_32x32x16_bf16 v[66:81], v[190:193], v[208:211], v[66:81]
	v_mfma_f32_32x32x16_bf16 v[50:65], v[196:199], v[204:207], v[50:65]
	v_mfma_f32_32x32x16_bf16 v[34:49], v[196:199], v[208:211], v[34:49]
	v_mfma_f32_32x32x16_bf16 v[18:33], v[200:203], v[204:207], v[18:33]
	v_mfma_f32_32x32x16_bf16 v[2:17], v[200:203], v[208:211], v[2:17]
	s_waitcnt lgkmcnt(1)
	v_mfma_f32_32x32x16_bf16 v[114:129], v[212:215], v[244:247], v[114:129]
	s_waitcnt lgkmcnt(0)
	v_mfma_f32_32x32x16_bf16 v[98:113], v[212:215], v[248:251], v[98:113]
	v_mfma_f32_32x32x16_bf16 v[82:97], v[216:219], v[244:247], v[82:97]
	v_mfma_f32_32x32x16_bf16 v[66:81], v[216:219], v[248:251], v[66:81]
	v_mfma_f32_32x32x16_bf16 v[50:65], v[232:235], v[244:247], v[50:65]
	v_mfma_f32_32x32x16_bf16 v[34:49], v[232:235], v[248:251], v[34:49]
	v_mfma_f32_32x32x16_bf16 v[18:33], v[236:239], v[244:247], v[18:33]
	v_mfma_f32_32x32x16_bf16 v[2:17], v[236:239], v[248:251], v[2:17]
	s_add_u32 s56, s56, 0x80
	s_addc_u32 s57, s57, 0
	s_add_u32 s58, s58, 0x80
	s_addc_u32 s59, s59, 0
	s_barrier
	s_waitcnt vmcnt(7)
	ds_write_b128 v184, v[134:137]
	s_waitcnt vmcnt(6)
	ds_write_b128 v184, v[138:141] offset:4608
	s_waitcnt vmcnt(5)
	ds_write_b128 v184, v[142:145] offset:9216
	s_waitcnt vmcnt(4)
	ds_write_b128 v184, v[146:149] offset:13824
	s_waitcnt vmcnt(3)
	ds_write_b128 v184, v[154:157] offset:18432
	s_waitcnt vmcnt(2)
	ds_write_b128 v184, v[150:153] offset:23040
	s_waitcnt vmcnt(1)
	ds_write_b128 v184, v[162:165] offset:27648
	s_waitcnt vmcnt(0)
	ds_write_b128 v184, v[158:161] offset:32256
	s_waitcnt lgkmcnt(0)
	s_barrier
	ds_read_b128 v[186:189], v182
	ds_read_b128 v[204:207], v166 offset:53248
	ds_read_b128 v[208:211], v166 offset:57344
	ds_read_b128 v[190:193], v182 offset:4608
	ds_read_b128 v[196:199], v182 offset:9216
	ds_read_b128 v[200:203], v0
	ds_read_b128 v[212:215], v182 offset:32
	ds_read_b128 v[244:247], v167 offset:53248
	ds_read_b128 v[248:251], v167 offset:57344
	ds_read_b128 v[216:219], v182 offset:4640
	ds_read_b128 v[232:235], v182 offset:9248
	ds_read_b128 v[236:239], v0 offset:32
	s_waitcnt lgkmcnt(10)
	v_mfma_f32_32x32x16_bf16 v[114:129], v[186:189], v[204:207], v[114:129]
	s_add_u32 m0, s96, -128
	s_nop 0
	s_waitcnt lgkmcnt(9)
	v_mfma_f32_32x32x16_bf16 v[98:113], v[186:189], v[208:211], v[98:113]
	global_load_lds_dwordx4 v130, s[58:59] offset:128
	ds_read_b128 v[186:189], v182 offset:64
	s_waitcnt lgkmcnt(9)
	v_mfma_f32_32x32x16_bf16 v[82:97], v[190:193], v[204:207], v[82:97]
	global_load_lds_dwordx4 v131, s[58:59] offset:1152
	v_mfma_f32_32x32x16_bf16 v[66:81], v[190:193], v[208:211], v[66:81]
	global_load_lds_dwordx4 v132, s[58:59] offset:2176
	ds_read_b128 v[190:193], v182 offset:4672
	s_waitcnt lgkmcnt(9)
	v_mfma_f32_32x32x16_bf16 v[50:65], v[196:199], v[204:207], v[50:65]
	global_load_lds_dwordx4 v133, s[58:59] offset:3200
	v_mfma_f32_32x32x16_bf16 v[34:49], v[196:199], v[208:211], v[34:49]
	global_load_dwordx4 v[134:137], v178, s[56:57] offset:128
	ds_read_b128 v[196:199], v182 offset:9280
	s_waitcnt lgkmcnt(9)
	v_mfma_f32_32x32x16_bf16 v[18:33], v[200:203], v[204:207], v[18:33]
	global_load_dwordx4 v[138:141], v179, s[56:57] offset:128
	v_mfma_f32_32x32x16_bf16 v[2:17], v[200:203], v[208:211], v[2:17]
	global_load_dwordx4 v[142:145], v180, s[56:57] offset:128
	ds_read_b128 v[200:203], v0 offset:64
	ds_read_b128 v[204:207], v168 offset:53248
	ds_read_b128 v[208:211], v168 offset:57344
	s_waitcnt lgkmcnt(10)
	v_mfma_f32_32x32x16_bf16 v[114:129], v[212:215], v[244:247], v[114:129]
	global_load_dwordx4 v[146:149], v181, s[56:57] offset:128
	s_waitcnt lgkmcnt(9)
	v_mfma_f32_32x32x16_bf16 v[98:113], v[212:215], v[248:251], v[98:113]
	global_load_dwordx4 v[154:157], v185, s[56:57] offset:128
	ds_read_b128 v[212:215], v182 offset:96
	s_waitcnt lgkmcnt(9)
	v_mfma_f32_32x32x16_bf16 v[82:97], v[216:219], v[244:247], v[82:97]
	global_load_dwordx4 v[150:153], v222, s[56:57] offset:128
	v_mfma_f32_32x32x16_bf16 v[66:81], v[216:219], v[248:251], v[66:81]
	global_load_dwordx4 v[162:165], v223, s[56:57] offset:128
	ds_read_b128 v[216:219], v182 offset:4704
	s_waitcnt lgkmcnt(9)
	v_mfma_f32_32x32x16_bf16 v[50:65], v[232:235], v[244:247], v[50:65]
	global_load_dwordx4 v[158:161], v227, s[56:57] offset:128
	v_mfma_f32_32x32x16_bf16 v[34:49], v[232:235], v[248:251], v[34:49]
	ds_read_b128 v[232:235], v182 offset:9312
	s_waitcnt lgkmcnt(9)
	v_mfma_f32_32x32x16_bf16 v[18:33], v[236:239], v[244:247], v[18:33]
	v_mfma_f32_32x32x16_bf16 v[2:17], v[236:239], v[248:251], v[2:17]
	ds_read_b128 v[236:239], v0 offset:96
	ds_read_b128 v[244:247], v169 offset:53248
	ds_read_b128 v[248:251], v169 offset:57344
	s_waitcnt lgkmcnt(7)
	v_mfma_f32_32x32x16_bf16 v[114:129], v[186:189], v[204:207], v[114:129]
	s_waitcnt lgkmcnt(6)
	v_mfma_f32_32x32x16_bf16 v[98:113], v[186:189], v[208:211], v[98:113]
	v_mfma_f32_32x32x16_bf16 v[82:97], v[190:193], v[204:207], v[82:97]
	v_mfma_f32_32x32x16_bf16 v[66:81], v[190:193], v[208:211], v[66:81]
	v_mfma_f32_32x32x16_bf16 v[50:65], v[196:199], v[204:207], v[50:65]
	v_mfma_f32_32x32x16_bf16 v[34:49], v[196:199], v[208:211], v[34:49]
	v_mfma_f32_32x32x16_bf16 v[18:33], v[200:203], v[204:207], v[18:33]
	v_mfma_f32_32x32x16_bf16 v[2:17], v[200:203], v[208:211], v[2:17]
	s_waitcnt lgkmcnt(1)
	v_mfma_f32_32x32x16_bf16 v[114:129], v[212:215], v[244:247], v[114:129]
	s_waitcnt lgkmcnt(0)
	v_mfma_f32_32x32x16_bf16 v[98:113], v[212:215], v[248:251], v[98:113]
	v_mfma_f32_32x32x16_bf16 v[82:97], v[216:219], v[244:247], v[82:97]
	v_mfma_f32_32x32x16_bf16 v[66:81], v[216:219], v[248:251], v[66:81]
	v_mfma_f32_32x32x16_bf16 v[50:65], v[232:235], v[244:247], v[50:65]
	v_mfma_f32_32x32x16_bf16 v[34:49], v[232:235], v[248:251], v[34:49]
	v_mfma_f32_32x32x16_bf16 v[18:33], v[236:239], v[244:247], v[18:33]
	v_mfma_f32_32x32x16_bf16 v[2:17], v[236:239], v[248:251], v[2:17]
	s_add_u32 s56, s56, 0x80
	s_addc_u32 s57, s57, 0
	s_add_u32 s58, s58, 0x80
	s_addc_u32 s59, s59, 0
	s_movk_i32 s94, 20

; __device__ __forceinline__ int tid_opaque() { int t = threadIdx.x; asm volatile("" : "+v"(t)); return t; }
; template <int MI, int NI>
; __device__ __forceinline__ void gemm_kloop(const bf16* __restrict__ A, size_t lda, const bf16* __restrict__ Bt, size_t ldb, int K,
;                                            f16v (&acc)[MI][NI], bf16* sA, bf16* sB) {
;   const int tid = tid_opaque(), lane = tid & 63, w = tid >> 6;
;   const int r = lane & 31, hh = lane >> 5;
;   const int wm = w >> 1, wn = w & 1;
;   const int lrow = tid >> 3, lseg = tid & 7;
;   u4v ra[2 * MI], rb[2 * NI];
;   const int KT = K >> 6;
; #pragma unroll
;   for (int i = 0; i < 2 * MI; ++i) ra[i] = *(const u4v*)(A + (size_t)(lrow + 32 * i) * lda + lseg * 8);
; #pragma unroll
;   for (int i = 0; i < 2 * NI; ++i) rb[i] = *(const u4v*)(Bt + (size_t)(lrow + 32 * i) * ldb + lseg * 8);
;   unsigned pfs = 0;
;   {
;     if (tid < 64 * MI) pfs ^= *(const unsigned*)(A + (size_t)tid * lda + 64) ^ *(const unsigned*)(A + (size_t)tid * lda + 128);
;     if (tid < 64 * NI) pfs ^= *(const unsigned*)(Bt + (size_t)tid * ldb + 64) ^ *(const unsigned*)(Bt + (size_t)tid * ldb + 128);
;   }
.LBB0_22:
	s_lshr_b32 s2, s0, 4
	s_and_b32 s20, s2, 48
	s_sub_i32 s2, 44, s20
	s_min_u32 s21, s2, 16
	s_lshl_b32 s2, s21, 2
	v_cvt_f32_ubyte0_e32 v0, s2
	v_rcp_iflag_f32_e32 v2, v0
	v_cvt_f32_ubyte0_e32 v3, s0
	s_and_b32 s22, s0, 0xff
	v_readlane_b32 s64, v252, 23
	v_mul_f32_e32 v2, v3, v2
	v_trunc_f32_e32 v2, v2
	v_cvt_u32_f32_e32 v4, v2
	v_fma_f32 v2, -v2, v0, v3
	v_cmp_ge_f32_e64 s[2:3], |v2|, v0
	s_cmp_lg_u64 s[2:3], 0
	v_readfirstlane_b32 s2, v4
	s_addc_u32 s2, s2, 0
	s_and_b32 s2, s2, 0xff
	s_lshl_b32 s2, s2, 2
	s_mul_i32 s21, s21, s2
	s_sub_i32 s3, s22, s21
	s_sext_i32_i16 s21, s3
	s_bfe_u32 s21, s21, 0x2001d
	s_add_i32 s21, s3, s21
	s_sext_i32_i16 s22, s21
	s_and_b32 s21, s21, 0xfffc
	s_sub_i32 s3, s3, s21
	s_add_i32 s2, s2, s88
	s_sext_i32_i16 s3, s3
	s_add_i32 s3, s2, s3
	s_ashr_i32 s2, s22, 2
	s_add_i32 s2, s20, s2
	s_lshl_b32 s20, s3, 8
	s_ashr_i32 s21, s20, 31
	s_lshl_b64 s[22:23], s[20:21], 11
	v_readlane_b32 s66, v252, 25
	v_mov_b32_e32 v18, v195
	v_readlane_b32 s67, v252, 26
	s_add_u32 s24, s66, s22
	s_addc_u32 s25, s67, s23
	v_ashrrev_i32_e32 v2, 3, v18
	v_lshlrev_b32_e32 v0, 4, v18
	v_and_b32_e32 v0, 0x70, v0
	v_ashrrev_i32_e32 v3, 31, v2
	v_lshl_add_u64 v[4:5], s[24:25], 0, v[0:1]
	v_lshlrev_b64 v[6:7], 11, v[2:3]
	s_mov_b64 s[24:25], 0x10000
	v_lshl_add_u64 v[10:11], v[6:7], 0, s[24:25]
	v_lshl_add_u64 v[8:9], v[4:5], 0, v[6:7]
	v_lshl_add_u64 v[12:13], v[4:5], 0, v[10:11]
	s_mov_b64 s[24:25], 0x20000
	global_load_dwordx4 v[130:133], v[8:9], off
	global_load_dwordx4 v[138:141], v[12:13], off
	v_lshl_add_u64 v[12:13], v[6:7], 0, s[24:25]
	s_mov_b64 s[24:25], 0x30000
	v_lshl_add_u64 v[16:17], v[6:7], 0, s[24:25]
	v_lshl_add_u64 v[14:15], v[4:5], 0, v[12:13]
	v_lshl_add_u64 v[4:5], v[4:5], 0, v[16:17]
	s_ashr_i32 s3, s2, 31
	global_load_dwordx4 v[142:145], v[14:15], off
	global_load_dwordx4 v[146:149], v[4:5], off
	v_add_co_u32_e32 v4, vcc, s62, v8
	s_lshl_b64 s[26:27], s[2:3], 18
	s_nop 0
	v_addc_co_u32_e32 v5, vcc, 0, v9, vcc
	s_mov_b32 s3, 0x50000
	v_add_co_u32_e32 v14, vcc, s3, v8
	s_add_u32 s28, s18, s26
	s_nop 0
	v_addc_co_u32_e32 v15, vcc, 0, v9, vcc
	global_load_dwordx4 v[150:153], v[4:5], off
	global_load_dwordx4 v[154:157], v[14:15], off
	v_add_co_u32_e32 v4, vcc, s92, v8
	s_addc_u32 s29, s19, s27
	s_nop 0
	v_addc_co_u32_e32 v5, vcc, 0, v9, vcc
	v_add_co_u32_e32 v8, vcc, s93, v8
	v_and_b32_e32 v3, 0xfffff9f, v18
	s_nop 0
	v_addc_co_u32_e32 v9, vcc, 0, v9, vcc
	global_load_dwordx4 v[158:161], v[4:5], off
	global_load_dwordx4 v[162:165], v[8:9], off
	v_lshl_add_u64 v[4:5], s[28:29], 0, v[0:1]
	v_lshl_add_u64 v[8:9], v[4:5], 0, v[6:7]
	v_lshl_add_u64 v[10:11], v[4:5], 0, v[10:11]
	v_lshl_add_u64 v[8:9], v[4:5], 0, v[12:13]
	v_lshl_add_u64 v[4:5], v[4:5], 0, v[16:17]
	v_mul_lo_u32 v8, v2, s33
	v_or_b32_e32 v2, 0x60, v18
	v_mul_lo_u32 v9, v3, s33
	v_mul_lo_u32 v10, v2, s33
	v_lshl_add_u64 v[2:3], v[6:7], 0, s[22:23]
	v_or_b32_e32 v2, v2, v0
	s_waitcnt vmcnt(31)
	v_lshl_add_u64 v[178:179], s[66:67], 0, v[2:3]
	v_lshl_add_u64 v[2:3], s[26:27], 0, v[6:7]
	v_lshrrev_b32_e32 v4, 1, v18
	v_and_b32_e32 v5, 0x5f, v18
	v_or_b32_e32 v2, v2, v0
	v_and_b32_e32 v4, 16, v4
	v_mul_u32_u24_e32 v5, 0x90, v5
	v_lshl_add_u64 v[180:181], s[18:19], 0, v[2:3]
	v_mov_b32_e32 v2, 0
	s_mov_b64 s[22:23], 0
	s_waitcnt vmcnt(30)
	v_add_u32_e32 v184, v0, v8
	v_add_u32_e32 v183, v4, v9
	v_add_u32_e32 v182, v4, v10
	v_add_u32_e32 v0, v4, v5
	v_readfirstlane_b32 s56, v178
	v_readfirstlane_b32 s57, v179
	v_readfirstlane_b32 s58, v180
	v_readfirstlane_b32 s59, v181
	v_readfirstlane_b32 s94, v195
	v_subrev_u32_e32 v178, s56, v178
	v_add_u32_e32 v179, 0x10000, v178
	v_add_u32_e32 v180, 0x20000, v178
	v_add_u32_e32 v181, 0x30000, v178
	v_add_u32_e32 v185, 0x40000, v178
	v_add_u32_e32 v222, 0x50000, v178
	v_add_u32_e32 v223, 0x60000, v178
	v_add_u32_e32 v227, 0x70000, v178
	s_lshr_b32 s94, s94, 6
	s_mul_i32 s95, s94, 0x4000
	s_sub_u32 s58, s58, s95
	s_subb_u32 s59, s59, 0
	s_lshl_b32 s96, s94, 12
	s_add_u32 s96, s96, 36864
	v_and_b32_e32 v170, 63, v195
	v_lshrrev_b32_e32 v171, 3, v170
	v_lshrrev_b32_e32 v172, 4, v170
	v_and_b32_e32 v173, 7, v170
	v_xor_b32_e32 v172, v172, v173
	v_lshlrev_b32_e32 v172, 4, v172
	v_lshrrev_b32_e32 v173, 6, v195
	v_lshl_add_u32 v170, v173, 5, v171
	v_mul_u32_u24_e32 v170, 0x800, v170
	v_add_u32_e32 v134, v170, v172
	v_xor_b32_e32 v172, 64, v172
	v_add_u32_e32 v170, v170, v172
	v_add_u32_e32 v135, 0x3c00, v170
	v_add_u32_e32 v136, 0x7800, v134
	v_add_u32_e32 v137, 0xb400, v170
	v_and_b32_e32 v170, 31, v195
	v_bfe_u32 v171, v195, 5, 1
	v_bfe_u32 v172, v170, 1, 3
	v_xor_b32_e32 v171, v171, v172
	v_lshlrev_b32_e32 v171, 4, v171
	v_bfe_u32 v172, v195, 6, 1
	v_lshl_add_u32 v172, v172, 6, v170
	v_lshl_add_u32 v166, v172, 7, v171
	v_xor_b32_e32 v167, 32, v166
	v_xor_b32_e32 v168, 64, v166
	v_xor_b32_e32 v169, 96, v166
	s_add_u32 m0, s96, 0
	s_nop 0
	global_load_lds_dwordx4 v134, s[58:59] offset:0
	global_load_lds_dwordx4 v135, s[58:59] offset:1024
	global_load_lds_dwordx4 v136, s[58:59] offset:2048
	global_load_lds_dwordx4 v137, s[58:59] offset:3072
	v_mov_b32_e32 v3, v2
	v_mov_b32_e32 v4, v2
	v_mov_b32_e32 v5, v2
	v_mov_b32_e32 v6, v2
	v_mov_b32_e32 v7, v2
	v_mov_b32_e32 v8, v2
	v_mov_b32_e32 v9, v2
	v_mov_b32_e32 v10, v2
	v_mov_b32_e32 v11, v2
	v_mov_b32_e32 v12, v2
	v_mov_b32_e32 v13, v2
	v_mov_b32_e32 v14, v2
	v_mov_b32_e32 v15, v2
	v_mov_b32_e32 v16, v2
	v_mov_b32_e32 v17, v2
	v_mov_b32_e32 v18, v2
	v_mov_b32_e32 v19, v2
	v_mov_b32_e32 v20, v2
	v_mov_b32_e32 v21, v2
	v_mov_b32_e32 v22, v2
	v_mov_b32_e32 v23, v2
	v_mov_b32_e32 v24, v2
	v_mov_b32_e32 v25, v2
	v_mov_b32_e32 v26, v2
	v_mov_b32_e32 v27, v2
	v_mov_b32_e32 v28, v2
; #define MFMA(a, b, c) __builtin_amdgcn_mfma_f32_32x32x16_bf16((a), (b), (c), 0, 0, 0)
; #define ZERO_ACC(acc, MI_, NI_)                 \
;   _Pragma("unroll") for (int mi = 0; mi < MI_; ++mi) \
;   _Pragma("unroll") for (int ni = 0; ni < NI_; ++ni) \
;   _Pragma("unroll") for (int e = 0; e < 16; ++e) acc[mi][ni][e] = 0.f;
; template <int MI, int NI>
; __device__ __forceinline__ void gemm_kloop(const bf16* __restrict__ A, size_t lda, const bf16* __restrict__ Bt, size_t ldb, int K,
;                                            f16v (&acc)[MI][NI], bf16* sA, bf16* sB) {
;     ...
;   for (int kt = 0; kt < KT; ++kt) {
;     __syncthreads();
; #pragma unroll
;     for (int i = 0; i < 2 * MI; ++i) *(u4v*)(sA + (lrow + 32 * i) * 72 + lseg * 8) = ra[i];
; #pragma unroll
;     for (int i = 0; i < 2 * NI; ++i) *(u4v*)(sB + (lrow + 32 * i) * 72 + lseg * 8) = rb[i];
;     __syncthreads();
;     if (kt + 3 < KT) {
;       const int k2 = (kt + 3) << 6;
;       if (tid < 64 * MI) pfs ^= *(const unsigned*)(A + (size_t)tid * lda + k2);
;       if (tid < 64 * NI) pfs ^= *(const unsigned*)(Bt + (size_t)tid * ldb + k2);
;     }
;     if (kt + 1 < KT) {
;       const int k0 = (kt + 1) << 6;
; #pragma unroll
;       for (int i = 0; i < 2 * MI; ++i) ra[i] = *(const u4v*)(A + (size_t)(lrow + 32 * i) * lda + k0 + lseg * 8);
; #pragma unroll
;       for (int i = 0; i < 2 * NI; ++i) rb[i] = *(const u4v*)(Bt + (size_t)(lrow + 32 * i) * ldb + k0 + lseg * 8);
;     }
; #pragma unroll
;     for (int ks = 0; ks < 4; ++ks) {
;       s8v a[MI], b[NI];
; #pragma unroll
;       for (int mi = 0; mi < MI; ++mi) a[mi] = *(const s8v*)(sA + (wm * 32 * MI + mi * 32 + r) * 72 + ks * 16 + hh * 8);
; #pragma unroll
;       for (int ni = 0; ni < NI; ++ni) b[ni] = *(const s8v*)(sB + (wn * 32 * NI + ni * 32 + r) * 72 + ks * 16 + hh * 8);
; #pragma unroll
;       for (int mi = 0; mi < MI; ++mi)
; #pragma unroll
;         for (int ni = 0; ni < NI; ++ni) acc[mi][ni] = MFMA(a[mi], b[ni], acc[mi][ni]);
; __device__ __forceinline__ void ffn1_tile(const Params& p, int mt, int nt, bf16* sA, bf16* sB) {
;     ...
;   ZERO_ACC(acc, 4, 2)
	v_mov_b32_e32 v29, v2
	v_mov_b32_e32 v30, v2
	v_mov_b32_e32 v31, v2
	v_mov_b32_e32 v32, v2
	v_mov_b32_e32 v33, v2
	v_mov_b32_e32 v34, v2
	v_mov_b32_e32 v35, v2
	v_mov_b32_e32 v36, v2
	v_mov_b32_e32 v37, v2
	v_mov_b32_e32 v38, v2
	v_mov_b32_e32 v39, v2
	v_mov_b32_e32 v40, v2
	v_mov_b32_e32 v41, v2
	v_mov_b32_e32 v42, v2
	v_mov_b32_e32 v43, v2
	v_mov_b32_e32 v44, v2
	v_mov_b32_e32 v45, v2
	v_mov_b32_e32 v46, v2
	v_mov_b32_e32 v47, v2
	v_mov_b32_e32 v48, v2
	v_mov_b32_e32 v49, v2
	v_mov_b32_e32 v50, v2
	v_mov_b32_e32 v51, v2
	v_mov_b32_e32 v52, v2
	v_mov_b32_e32 v53, v2
	v_mov_b32_e32 v54, v2
	v_mov_b32_e32 v55, v2
	v_mov_b32_e32 v56, v2
	v_mov_b32_e32 v57, v2
	v_mov_b32_e32 v58, v2
	v_mov_b32_e32 v59, v2
	v_mov_b32_e32 v60, v2
	v_mov_b32_e32 v61, v2
	v_mov_b32_e32 v62, v2
	v_mov_b32_e32 v63, v2
	v_mov_b32_e32 v64, v2
	v_mov_b32_e32 v65, v2
	v_mov_b32_e32 v66, v2
	v_mov_b32_e32 v67, v2
	v_mov_b32_e32 v68, v2
	v_mov_b32_e32 v69, v2
	v_mov_b32_e32 v70, v2
	v_mov_b32_e32 v71, v2
	v_mov_b32_e32 v72, v2
	v_mov_b32_e32 v73, v2
	v_mov_b32_e32 v74, v2
	v_mov_b32_e32 v75, v2
	v_mov_b32_e32 v76, v2
	v_mov_b32_e32 v77, v2
	v_mov_b32_e32 v78, v2
	v_mov_b32_e32 v79, v2
	v_mov_b32_e32 v80, v2
	v_mov_b32_e32 v81, v2
	v_mov_b32_e32 v82, v2
	v_mov_b32_e32 v83, v2
	v_mov_b32_e32 v84, v2
	v_mov_b32_e32 v85, v2
	v_mov_b32_e32 v86, v2
	v_mov_b32_e32 v87, v2
	v_mov_b32_e32 v88, v2
	v_mov_b32_e32 v89, v2
	v_mov_b32_e32 v90, v2
	v_mov_b32_e32 v91, v2
	v_mov_b32_e32 v92, v2
	v_mov_b32_e32 v93, v2
	v_mov_b32_e32 v94, v2
	v_mov_b32_e32 v95, v2
	v_mov_b32_e32 v96, v2
	v_mov_b32_e32 v97, v2
	v_mov_b32_e32 v98, v2
	v_mov_b32_e32 v99, v2
	v_mov_b32_e32 v100, v2
	v_mov_b32_e32 v101, v2
	v_mov_b32_e32 v102, v2
	v_mov_b32_e32 v103, v2
	v_mov_b32_e32 v104, v2
	v_mov_b32_e32 v105, v2
	v_mov_b32_e32 v106, v2
	v_mov_b32_e32 v107, v2
	v_mov_b32_e32 v108, v2
	v_mov_b32_e32 v109, v2
	v_mov_b32_e32 v110, v2
	v_mov_b32_e32 v111, v2
	v_mov_b32_e32 v112, v2
	v_mov_b32_e32 v113, v2
	v_mov_b32_e32 v114, v2
	v_mov_b32_e32 v115, v2
	v_mov_b32_e32 v116, v2
	v_mov_b32_e32 v117, v2
	v_mov_b32_e32 v118, v2
	v_mov_b32_e32 v119, v2
	v_mov_b32_e32 v120, v2
	v_mov_b32_e32 v121, v2
	v_mov_b32_e32 v122, v2
	v_mov_b32_e32 v123, v2
	v_mov_b32_e32 v124, v2
	v_mov_b32_e32 v125, v2
	v_mov_b32_e32 v126, v2
	v_mov_b32_e32 v127, v2
	v_mov_b32_e32 v128, v2
	v_mov_b32_e32 v129, v2
	v_readlane_b32 s65, v252, 24
	v_readlane_b32 s68, v252, 27
	v_readlane_b32 s69, v252, 28
	v_readlane_b32 s70, v252, 29
	v_readlane_b32 s71, v252, 30
	v_readlane_b32 s72, v252, 31
	v_readlane_b32 s73, v252, 32
	v_readlane_b32 s74, v252, 33
	v_readlane_b32 s75, v252, 34
	v_readlane_b32 s76, v252, 35
	v_readlane_b32 s77, v252, 36
	v_readlane_b32 s78, v252, 37
	v_readlane_b32 s79, v252, 38
	s_barrier
	s_waitcnt vmcnt(11)
	ds_write_b128 v184, v[130:133]
	s_waitcnt vmcnt(10)
	ds_write_b128 v184, v[138:141] offset:4608
	s_waitcnt vmcnt(9)
	ds_write_b128 v184, v[142:145] offset:9216
	s_waitcnt vmcnt(8)
	ds_write_b128 v184, v[146:149] offset:13824
	s_waitcnt vmcnt(7)
	ds_write_b128 v184, v[150:153] offset:18432
	s_waitcnt vmcnt(6)
	ds_write_b128 v184, v[154:157] offset:23040
	s_waitcnt vmcnt(5)
	ds_write_b128 v184, v[158:161] offset:27648
	s_waitcnt vmcnt(4)
	ds_write_b128 v184, v[162:165] offset:32256
	s_waitcnt vmcnt(0) lgkmcnt(0)
	s_barrier
	ds_read_b128 v[186:189], v183
	ds_read_b128 v[204:207], v166 offset:36864
	ds_read_b128 v[208:211], v166 offset:40960
	ds_read_b128 v[190:193], v183 offset:4608
	ds_read_b128 v[196:199], v183 offset:9216
	ds_read_b128 v[200:203], v182
	ds_read_b128 v[212:215], v183 offset:32
	ds_read_b128 v[244:247], v167 offset:36864
	ds_read_b128 v[248:251], v167 offset:40960
	ds_read_b128 v[216:219], v183 offset:4640
	ds_read_b128 v[232:235], v183 offset:9248
	ds_read_b128 v[236:239], v182 offset:32
	s_waitcnt lgkmcnt(10)
	v_mfma_f32_32x32x16_bf16 v[114:129], v[186:189], v[204:207], v[114:129]
	s_add_u32 m0, s96, 16256
	s_nop 0
	s_waitcnt lgkmcnt(9)
	v_mfma_f32_32x32x16_bf16 v[98:113], v[186:189], v[208:211], v[98:113]
	global_load_lds_dwordx4 v134, s[58:59] offset:128
	ds_read_b128 v[186:189], v183 offset:64
	s_waitcnt lgkmcnt(9)
	v_mfma_f32_32x32x16_bf16 v[82:97], v[190:193], v[204:207], v[82:97]
	global_load_lds_dwordx4 v135, s[58:59] offset:1152
	v_mfma_f32_32x32x16_bf16 v[66:81], v[190:193], v[208:211], v[66:81]
	global_load_lds_dwordx4 v136, s[58:59] offset:2176
	ds_read_b128 v[190:193], v183 offset:4672
	s_waitcnt lgkmcnt(9)
	v_mfma_f32_32x32x16_bf16 v[50:65], v[196:199], v[204:207], v[50:65]
	global_load_lds_dwordx4 v137, s[58:59] offset:3200
	v_mfma_f32_32x32x16_bf16 v[34:49], v[196:199], v[208:211], v[34:49]
	global_load_dwordx4 v[130:133], v178, s[56:57] offset:128
	ds_read_b128 v[196:199], v183 offset:9280
	s_waitcnt lgkmcnt(9)
	v_mfma_f32_32x32x16_bf16 v[18:33], v[200:203], v[204:207], v[18:33]
	global_load_dwordx4 v[138:141], v179, s[56:57] offset:128
	v_mfma_f32_32x32x16_bf16 v[2:17], v[200:203], v[208:211], v[2:17]
	global_load_dwordx4 v[142:145], v180, s[56:57] offset:128
	ds_read_b128 v[200:203], v182 offset:64
	ds_read_b128 v[204:207], v168 offset:36864
	ds_read_b128 v[208:211], v168 offset:40960
	s_waitcnt lgkmcnt(10)
	v_mfma_f32_32x32x16_bf16 v[114:129], v[212:215], v[244:247], v[114:129]
	global_load_dwordx4 v[146:149], v181, s[56:57] offset:128
	s_waitcnt lgkmcnt(9)
	v_mfma_f32_32x32x16_bf16 v[98:113], v[212:215], v[248:251], v[98:113]
	global_load_dwordx4 v[150:153], v185, s[56:57] offset:128
	ds_read_b128 v[212:215], v183 offset:96
	s_waitcnt lgkmcnt(9)
; #define MFMA(a, b, c) __builtin_amdgcn_mfma_f32_32x32x16_bf16((a), (b), (c), 0, 0, 0)
; template <int MI, int NI>
; __device__ __forceinline__ void gemm_kloop(const bf16* __restrict__ A, size_t lda, const bf16* __restrict__ Bt, size_t ldb, int K,
;                                            f16v (&acc)[MI][NI], bf16* sA, bf16* sB) {
;     ...
;   for (int kt = 0; kt < KT; ++kt) {
;     __syncthreads();
; #pragma unroll
;     for (int i = 0; i < 2 * MI; ++i) *(u4v*)(sA + (lrow + 32 * i) * 72 + lseg * 8) = ra[i];
; #pragma unroll
;     for (int i = 0; i < 2 * NI; ++i) *(u4v*)(sB + (lrow + 32 * i) * 72 + lseg * 8) = rb[i];
;     __syncthreads();
;     if (kt + 3 < KT) {
;       const int k2 = (kt + 3) << 6;
;       if (tid < 64 * MI) pfs ^= *(const unsigned*)(A + (size_t)tid * lda + k2);
;       if (tid < 64 * NI) pfs ^= *(const unsigned*)(Bt + (size_t)tid * ldb + k2);
;     }
;     if (kt + 1 < KT) {
;       const int k0 = (kt + 1) << 6;
; #pragma unroll
;       for (int i = 0; i < 2 * MI; ++i) ra[i] = *(const u4v*)(A + (size_t)(lrow + 32 * i) * lda + k0 + lseg * 8);
; #pragma unroll
;       for (int i = 0; i < 2 * NI; ++i) rb[i] = *(const u4v*)(Bt + (size_t)(lrow + 32 * i) * ldb + k0 + lseg * 8);
;     }
; #pragma unroll
;     for (int ks = 0; ks < 4; ++ks) {
;       s8v a[MI], b[NI];
; #pragma unroll
;       for (int mi = 0; mi < MI; ++mi) a[mi] = *(const s8v*)(sA + (wm * 32 * MI + mi * 32 + r) * 72 + ks * 16 + hh * 8);
; #pragma unroll
;       for (int ni = 0; ni < NI; ++ni) b[ni] = *(const s8v*)(sB + (wn * 32 * NI + ni * 32 + r) * 72 + ks * 16 + hh * 8);
; #pragma unroll
;       for (int mi = 0; mi < MI; ++mi)
; #pragma unroll
;         for (int ni = 0; ni < NI; ++ni) acc[mi][ni] = MFMA(a[mi], b[ni], acc[mi][ni]);
;     }
	v_mfma_f32_32x32x16_bf16 v[82:97], v[216:219], v[244:247], v[82:97]
	global_load_dwordx4 v[154:157], v222, s[56:57] offset:128
	v_mfma_f32_32x32x16_bf16 v[66:81], v[216:219], v[248:251], v[66:81]
	global_load_dwordx4 v[158:161], v223, s[56:57] offset:128
	ds_read_b128 v[216:219], v183 offset:4704
	s_waitcnt lgkmcnt(9)
	v_mfma_f32_32x32x16_bf16 v[50:65], v[232:235], v[244:247], v[50:65]
	global_load_dwordx4 v[162:165], v227, s[56:57] offset:128
	v_mfma_f32_32x32x16_bf16 v[34:49], v[232:235], v[248:251], v[34:49]
	ds_read_b128 v[232:235], v183 offset:9312
	s_waitcnt lgkmcnt(9)
	v_mfma_f32_32x32x16_bf16 v[18:33], v[236:239], v[244:247], v[18:33]
	v_mfma_f32_32x32x16_bf16 v[2:17], v[236:239], v[248:251], v[2:17]
	ds_read_b128 v[236:239], v182 offset:96
	ds_read_b128 v[244:247], v169 offset:36864
	ds_read_b128 v[248:251], v169 offset:40960
	s_waitcnt lgkmcnt(7)
	v_mfma_f32_32x32x16_bf16 v[114:129], v[186:189], v[204:207], v[114:129]
	s_waitcnt lgkmcnt(6)
	v_mfma_f32_32x32x16_bf16 v[98:113], v[186:189], v[208:211], v[98:113]
	v_mfma_f32_32x32x16_bf16 v[82:97], v[190:193], v[204:207], v[82:97]
	v_mfma_f32_32x32x16_bf16 v[66:81], v[190:193], v[208:211], v[66:81]
	v_mfma_f32_32x32x16_bf16 v[50:65], v[196:199], v[204:207], v[50:65]
	v_mfma_f32_32x32x16_bf16 v[34:49], v[196:199], v[208:211], v[34:49]
	v_mfma_f32_32x32x16_bf16 v[2:17], v[200:203], v[208:211], v[2:17]
	v_mfma_f32_32x32x16_bf16 v[18:33], v[200:203], v[204:207], v[18:33]
	s_waitcnt lgkmcnt(1)
	v_mfma_f32_32x32x16_bf16 v[114:129], v[212:215], v[244:247], v[114:129]
	s_waitcnt lgkmcnt(0)
	v_mfma_f32_32x32x16_bf16 v[98:113], v[212:215], v[248:251], v[98:113]
	v_mfma_f32_32x32x16_bf16 v[82:97], v[216:219], v[244:247], v[82:97]
	v_mfma_f32_32x32x16_bf16 v[66:81], v[216:219], v[248:251], v[66:81]
	v_mfma_f32_32x32x16_bf16 v[50:65], v[232:235], v[244:247], v[50:65]
	v_mfma_f32_32x32x16_bf16 v[34:49], v[232:235], v[248:251], v[34:49]
	v_mfma_f32_32x32x16_bf16 v[18:33], v[236:239], v[244:247], v[18:33]
	v_mfma_f32_32x32x16_bf16 v[2:17], v[236:239], v[248:251], v[2:17]
	s_add_u32 s56, s56, 0x80
	s_addc_u32 s57, s57, 0
	s_add_u32 s58, s58, 0x80
	s_addc_u32 s59, s59, 0
	s_barrier
	s_waitcnt vmcnt(7)
	ds_write_b128 v184, v[130:133]
	s_waitcnt vmcnt(6)
	ds_write_b128 v184, v[138:141] offset:4608
	s_waitcnt vmcnt(5)
	ds_write_b128 v184, v[142:145] offset:9216
	s_waitcnt vmcnt(4)
	ds_write_b128 v184, v[146:149] offset:13824
	s_waitcnt vmcnt(3)
	ds_write_b128 v184, v[150:153] offset:18432
	s_waitcnt vmcnt(2)
	ds_write_b128 v184, v[154:157] offset:23040
	s_waitcnt vmcnt(1)
	ds_write_b128 v184, v[158:161] offset:27648
	s_waitcnt vmcnt(0)
	ds_write_b128 v184, v[162:165] offset:32256
	s_waitcnt lgkmcnt(0)
	s_barrier
; #define MFMA(a, b, c) __builtin_amdgcn_mfma_f32_32x32x16_bf16((a), (b), (c), 0, 0, 0)
; template <int MI, int NI>
; __device__ __forceinline__ void gemm_kloop(const bf16* __restrict__ A, size_t lda, const bf16* __restrict__ Bt, size_t ldb, int K,
;                                            f16v (&acc)[MI][NI], bf16* sA, bf16* sB) {
;     ...
;   for (int kt = 0; kt < KT; ++kt) {
;     __syncthreads();
; #pragma unroll
;     for (int i = 0; i < 2 * MI; ++i) *(u4v*)(sA + (lrow + 32 * i) * 72 + lseg * 8) = ra[i];
; #pragma unroll
;     for (int i = 0; i < 2 * NI; ++i) *(u4v*)(sB + (lrow + 32 * i) * 72 + lseg * 8) = rb[i];
;     __syncthreads();
;     if (kt + 3 < KT) {
;       const int k2 = (kt + 3) << 6;
;       if (tid < 64 * MI) pfs ^= *(const unsigned*)(A + (size_t)tid * lda + k2);
;       if (tid < 64 * NI) pfs ^= *(const unsigned*)(Bt + (size_t)tid * ldb + k2);
;     }
;     if (kt + 1 < KT) {
;       const int k0 = (kt + 1) << 6;
; #pragma unroll
;       for (int i = 0; i < 2 * MI; ++i) ra[i] = *(const u4v*)(A + (size_t)(lrow + 32 * i) * lda + k0 + lseg * 8);
; #pragma unroll
;       for (int i = 0; i < 2 * NI; ++i) rb[i] = *(const u4v*)(Bt + (size_t)(lrow + 32 * i) * ldb + k0 + lseg * 8);
;     }
; #pragma unroll
;     for (int ks = 0; ks < 4; ++ks) {
;       s8v a[MI], b[NI];
; #pragma unroll
;       for (int mi = 0; mi < MI; ++mi) a[mi] = *(const s8v*)(sA + (wm * 32 * MI + mi * 32 + r) * 72 + ks * 16 + hh * 8);
; #pragma unroll
;       for (int ni = 0; ni < NI; ++ni) b[ni] = *(const s8v*)(sB + (wn * 32 * NI + ni * 32 + r) * 72 + ks * 16 + hh * 8);
; #pragma unroll
;       for (int mi = 0; mi < MI; ++mi)
; #pragma unroll
;         for (int ni = 0; ni < NI; ++ni) acc[mi][ni] = MFMA(a[mi], b[ni], acc[mi][ni]);
;     }
	ds_read_b128 v[186:189], v183
	ds_read_b128 v[204:207], v166 offset:53248
	ds_read_b128 v[208:211], v166 offset:57344
	ds_read_b128 v[190:193], v183 offset:4608
	ds_read_b128 v[196:199], v183 offset:9216
	ds_read_b128 v[200:203], v182
	ds_read_b128 v[212:215], v183 offset:32
	ds_read_b128 v[244:247], v167 offset:53248
	ds_read_b128 v[248:251], v167 offset:57344
	ds_read_b128 v[216:219], v183 offset:4640
	ds_read_b128 v[232:235], v183 offset:9248
	ds_read_b128 v[236:239], v182 offset:32
	s_waitcnt lgkmcnt(10)
	v_mfma_f32_32x32x16_bf16 v[114:129], v[186:189], v[204:207], v[114:129]
	s_add_u32 m0, s96, -128
	s_nop 0
	s_waitcnt lgkmcnt(9)
	v_mfma_f32_32x32x16_bf16 v[98:113], v[186:189], v[208:211], v[98:113]
	global_load_lds_dwordx4 v134, s[58:59] offset:128
	ds_read_b128 v[186:189], v183 offset:64
	s_waitcnt lgkmcnt(9)
	v_mfma_f32_32x32x16_bf16 v[82:97], v[190:193], v[204:207], v[82:97]
	global_load_lds_dwordx4 v135, s[58:59] offset:1152
	v_mfma_f32_32x32x16_bf16 v[66:81], v[190:193], v[208:211], v[66:81]
	global_load_lds_dwordx4 v136, s[58:59] offset:2176
	ds_read_b128 v[190:193], v183 offset:4672
	s_waitcnt lgkmcnt(9)
	v_mfma_f32_32x32x16_bf16 v[50:65], v[196:199], v[204:207], v[50:65]
	global_load_lds_dwordx4 v137, s[58:59] offset:3200
	v_mfma_f32_32x32x16_bf16 v[34:49], v[196:199], v[208:211], v[34:49]
	global_load_dwordx4 v[130:133], v178, s[56:57] offset:128
	ds_read_b128 v[196:199], v183 offset:9280
	s_waitcnt lgkmcnt(9)
	v_mfma_f32_32x32x16_bf16 v[18:33], v[200:203], v[204:207], v[18:33]
	global_load_dwordx4 v[138:141], v179, s[56:57] offset:128
	v_mfma_f32_32x32x16_bf16 v[2:17], v[200:203], v[208:211], v[2:17]
	global_load_dwordx4 v[142:145], v180, s[56:57] offset:128
	ds_read_b128 v[200:203], v182 offset:64
	ds_read_b128 v[204:207], v168 offset:53248
	ds_read_b128 v[208:211], v168 offset:57344
	s_waitcnt lgkmcnt(10)
	v_mfma_f32_32x32x16_bf16 v[114:129], v[212:215], v[244:247], v[114:129]
	global_load_dwordx4 v[146:149], v181, s[56:57] offset:128
	s_waitcnt lgkmcnt(9)
	v_mfma_f32_32x32x16_bf16 v[98:113], v[212:215], v[248:251], v[98:113]
	global_load_dwordx4 v[150:153], v185, s[56:57] offset:128
	ds_read_b128 v[212:215], v183 offset:96
	s_waitcnt lgkmcnt(9)
	v_mfma_f32_32x32x16_bf16 v[82:97], v[216:219], v[244:247], v[82:97]
	global_load_dwordx4 v[154:157], v222, s[56:57] offset:128
	v_mfma_f32_32x32x16_bf16 v[66:81], v[216:219], v[248:251], v[66:81]
	global_load_dwordx4 v[158:161], v223, s[56:57] offset:128
	ds_read_b128 v[216:219], v183 offset:4704
	s_waitcnt lgkmcnt(9)
	v_mfma_f32_32x32x16_bf16 v[50:65], v[232:235], v[244:247], v[50:65]
	global_load_dwordx4 v[162:165], v227, s[56:57] offset:128
	v_mfma_f32_32x32x16_bf16 v[34:49], v[232:235], v[248:251], v[34:49]
	ds_read_b128 v[232:235], v183 offset:9312
	s_waitcnt lgkmcnt(9)
	v_mfma_f32_32x32x16_bf16 v[18:33], v[236:239], v[244:247], v[18:33]
	v_mfma_f32_32x32x16_bf16 v[2:17], v[236:239], v[248:251], v[2:17]
	ds_read_b128 v[236:239], v182 offset:96
	ds_read_b128 v[244:247], v169 offset:53248
	ds_read_b128 v[248:251], v169 offset:57344
	s_waitcnt lgkmcnt(7)
	v_mfma_f32_32x32x16_bf16 v[114:129], v[186:189], v[204:207], v[114:129]
	s_waitcnt lgkmcnt(6)
	v_mfma_f32_32x32x16_bf16 v[98:113], v[186:189], v[208:211], v[98:113]
	v_mfma_f32_32x32x16_bf16 v[82:97], v[190:193], v[204:207], v[82:97]
	v_mfma_f32_32x32x16_bf16 v[66:81], v[190:193], v[208:211], v[66:81]
	v_mfma_f32_32x32x16_bf16 v[50:65], v[196:199], v[204:207], v[50:65]
	v_mfma_f32_32x32x16_bf16 v[34:49], v[196:199], v[208:211], v[34:49]
	v_mfma_f32_32x32x16_bf16 v[2:17], v[200:203], v[208:211], v[2:17]
	v_mfma_f32_32x32x16_bf16 v[18:33], v[200:203], v[204:207], v[18:33]
	s_waitcnt lgkmcnt(1)
	v_mfma_f32_32x32x16_bf16 v[114:129], v[212:215], v[244:247], v[114:129]
	s_waitcnt lgkmcnt(0)
	v_mfma_f32_32x32x16_bf16 v[98:113], v[212:215], v[248:251], v[98:113]
	v_mfma_f32_32x32x16_bf16 v[82:97], v[216:219], v[244:247], v[82:97]
	v_mfma_f32_32x32x16_bf16 v[66:81], v[216:219], v[248:251], v[66:81]
	v_mfma_f32_32x32x16_bf16 v[50:65], v[232:235], v[244:247], v[50:65]
	v_mfma_f32_32x32x16_bf16 v[34:49], v[232:235], v[248:251], v[34:49]
	v_mfma_f32_32x32x16_bf16 v[18:33], v[236:239], v[244:247], v[18:33]
	v_mfma_f32_32x32x16_bf16 v[2:17], v[236:239], v[248:251], v[2:17]
	s_add_u32 s56, s56, 0x80
	s_addc_u32 s57, s57, 0
	s_add_u32 s58, s58, 0x80
	s_addc_u32 s59, s59, 0
	s_movk_i32 s94, 6

; __device__ __forceinline__ int tid_opaque() { int t = threadIdx.x; asm volatile("" : "+v"(t)); return t; }
; template <int MI, int NI>
; __device__ __forceinline__ void gemm_kloop(const bf16* __restrict__ A, size_t lda, const bf16* __restrict__ Bt, size_t ldb, int K,
;                                            f16v (&acc)[MI][NI], bf16* sA, bf16* sB) {
;   const int tid = tid_opaque(), lane = tid & 63, w = tid >> 6;
;   const int r = lane & 31, hh = lane >> 5;
;   const int wm = w >> 1, wn = w & 1;
;   const int lrow = tid >> 3, lseg = tid & 7;
;   u4v ra[2 * MI], rb[2 * NI];
;   const int KT = K >> 6;
; #pragma unroll
;   for (int i = 0; i < 2 * MI; ++i) ra[i] = *(const u4v*)(A + (size_t)(lrow + 32 * i) * lda + lseg * 8);
; #pragma unroll
;   for (int i = 0; i < 2 * NI; ++i) rb[i] = *(const u4v*)(Bt + (size_t)(lrow + 32 * i) * ldb + lseg * 8);
.LBB0_38:
	s_lshr_b32 s20, s0, 3
	s_and_b32 s30, s20, 12
	s_lshl_b32 s20, s30, 3
	s_sub_i32 s20, s0, s20
	s_bfe_i32 s22, s20, 0x80000
	s_bfe_u32 s22, s22, 0x2000d
	s_add_i32 s22, s20, s22
	s_bfe_i32 s23, s22, 0x80000
	s_and_b32 s22, s22, 0xfc
	s_sub_i32 s20, s20, s22
	s_or_b32 s21, s30, s88
	s_sext_i32_i8 s31, s20
	s_add_i32 s21, s21, s31
	s_sext_i32_i16 s23, s23
	s_lshl_b32 s22, s21, 8
	s_lshl_b32 s20, s23, 5
	s_ashr_i32 s23, s22, 31
	v_readlane_b32 s36, v252, 15
	s_and_b32 s20, s20, 0xffffff80
	s_lshl_b64 s[24:25], s[22:23], 11
	v_readlane_b32 s42, v252, 21
	v_mov_b32_e32 v18, v195
	v_readlane_b32 s43, v252, 22
	s_add_u32 s24, s42, s24
	s_addc_u32 s25, s43, s25
	v_ashrrev_i32_e32 v2, 3, v18
	v_lshlrev_b32_e32 v0, 4, v18
	v_and_b32_e32 v0, 0x70, v0
	v_ashrrev_i32_e32 v3, 31, v2
	v_lshl_add_u64 v[4:5], s[24:25], 0, v[0:1]
	v_lshlrev_b64 v[6:7], 11, v[2:3]
	s_mov_b64 s[24:25], 0x10000
	v_lshl_add_u64 v[10:11], v[6:7], 0, s[24:25]
	v_lshl_add_u64 v[8:9], v[4:5], 0, v[6:7]
	v_lshl_add_u64 v[12:13], v[4:5], 0, v[10:11]
	s_mov_b64 s[24:25], 0x20000
	global_load_dwordx4 v[130:133], v[8:9], off
	global_load_dwordx4 v[138:141], v[12:13], off
	v_lshl_add_u64 v[12:13], v[6:7], 0, s[24:25]
	s_mov_b64 s[24:25], 0x30000
	v_lshl_add_u64 v[16:17], v[6:7], 0, s[24:25]
	v_lshl_add_u64 v[14:15], v[4:5], 0, v[12:13]
	v_lshl_add_u64 v[4:5], v[4:5], 0, v[16:17]
	global_load_dwordx4 v[142:145], v[14:15], off
	global_load_dwordx4 v[146:149], v[4:5], off
	v_add_co_u32_e32 v4, vcc, s62, v8
	s_mov_b32 s23, 0x50000
	s_nop 0
	v_addc_co_u32_e32 v5, vcc, 0, v9, vcc
	v_add_co_u32_e32 v14, vcc, s23, v8
	s_ashr_i32 s21, s20, 31
	s_nop 0
	v_addc_co_u32_e32 v15, vcc, 0, v9, vcc
	s_lshl_b64 s[26:27], s[20:21], 11
	global_load_dwordx4 v[150:153], v[4:5], off
	global_load_dwordx4 v[154:157], v[14:15], off
	v_add_co_u32_e32 v4, vcc, s92, v8
	s_add_u32 s28, s16, s26
	s_nop 0
	v_addc_co_u32_e32 v5, vcc, 0, v9, vcc
	s_addc_u32 s29, s17, s27
	v_add_co_u32_e32 v8, vcc, s93, v8
	s_add_i32 s21, s88, s30
	s_nop 0
	v_addc_co_u32_e32 v9, vcc, 0, v9, vcc
	global_load_dwordx4 v[158:161], v[4:5], off
	global_load_dwordx4 v[162:165], v[8:9], off
	v_lshl_add_u64 v[4:5], s[28:29], 0, v[0:1]
	v_lshl_add_u64 v[8:9], v[4:5], 0, v[6:7]
	v_lshl_add_u64 v[10:11], v[4:5], 0, v[10:11]
	v_lshl_add_u64 v[8:9], v[4:5], 0, v[12:13]
	v_lshl_add_u64 v[4:5], v[4:5], 0, v[16:17]
	s_add_i32 s21, s21, s31
	s_lshl_b32 s24, s21, 8
	s_ashr_i32 s25, s24, 31
	v_and_b32_e32 v3, 0xfffff9f, v18
	v_mul_lo_u32 v8, v2, s33
	v_or_b32_e32 v2, 0x60, v18
	s_lshl_b64 s[24:25], s[24:25], 11
	v_mul_lo_u32 v9, v3, s33
	v_mul_lo_u32 v10, v2, s33
	v_lshl_add_u64 v[2:3], v[6:7], 0, s[24:25]
	v_or_b32_e32 v2, v2, v0
	s_waitcnt vmcnt(31)
	v_lshl_add_u64 v[178:179], s[42:43], 0, v[2:3]
	v_lshl_add_u64 v[2:3], v[6:7], 0, s[26:27]
	v_lshrrev_b32_e32 v4, 1, v18
	v_and_b32_e32 v5, 0x5f, v18
	v_or_b32_e32 v2, v2, v0
	v_and_b32_e32 v4, 16, v4
	v_mul_u32_u24_e32 v5, 0x90, v5
	v_lshl_add_u64 v[180:181], s[16:17], 0, v[2:3]
	v_mov_b32_e32 v2, 0
	s_mov_b64 s[24:25], 0
	s_waitcnt vmcnt(30)
	v_add_u32_e32 v184, v0, v8
	v_add_u32_e32 v182, v4, v9
	v_add_u32_e32 v0, v4, v10
	v_add_u32_e32 v183, v4, v5
	v_readfirstlane_b32 s56, v178
	v_readfirstlane_b32 s57, v179
	v_readfirstlane_b32 s58, v180
	v_readfirstlane_b32 s59, v181
	v_readfirstlane_b32 s94, v195
	v_subrev_u32_e32 v178, s56, v178
	v_add_u32_e32 v179, 0x10000, v178
	v_add_u32_e32 v180, 0x20000, v178
	v_add_u32_e32 v181, 0x30000, v178
	v_add_u32_e32 v185, 0x40000, v178
	v_add_u32_e32 v222, 0x50000, v178
	v_add_u32_e32 v223, 0x60000, v178
	v_add_u32_e32 v227, 0x70000, v178
	s_lshr_b32 s94, s94, 6
	s_mul_i32 s95, s94, 0x4000
	s_sub_u32 s58, s58, s95
	s_subb_u32 s59, s59, 0
	s_lshl_b32 s96, s94, 12
	s_add_u32 s96, s96, 36864
	v_and_b32_e32 v170, 63, v195
	v_lshrrev_b32_e32 v171, 3, v170
	v_lshrrev_b32_e32 v172, 4, v170
	v_and_b32_e32 v173, 7, v170
	v_xor_b32_e32 v172, v172, v173
	v_lshlrev_b32_e32 v172, 4, v172
	v_lshrrev_b32_e32 v173, 6, v195
	v_lshl_add_u32 v170, v173, 5, v171
	v_mul_u32_u24_e32 v170, 0x800, v170
	v_add_u32_e32 v134, v170, v172
	v_xor_b32_e32 v172, 64, v172
	v_add_u32_e32 v170, v170, v172
	v_add_u32_e32 v135, 0x3c00, v170
	v_add_u32_e32 v136, 0x7800, v134
	v_add_u32_e32 v137, 0xb400, v170
	v_and_b32_e32 v170, 31, v195
	v_bfe_u32 v171, v195, 5, 1
	v_bfe_u32 v172, v170, 1, 3
	v_xor_b32_e32 v171, v171, v172
	v_lshlrev_b32_e32 v171, 4, v171
	v_bfe_u32 v172, v195, 6, 1
	v_lshl_add_u32 v172, v172, 6, v170
	v_lshl_add_u32 v166, v172, 7, v171
	v_xor_b32_e32 v167, 32, v166
	v_xor_b32_e32 v168, 64, v166
	v_xor_b32_e32 v169, 96, v166
	s_add_u32 m0, s96, 0
	s_nop 0
	global_load_lds_dwordx4 v134, s[58:59] offset:0
	global_load_lds_dwordx4 v135, s[58:59] offset:1024
	global_load_lds_dwordx4 v136, s[58:59] offset:2048
	global_load_lds_dwordx4 v137, s[58:59] offset:3072
	v_mov_b32_e32 v3, v2
	v_mov_b32_e32 v4, v2
	v_mov_b32_e32 v5, v2
	v_mov_b32_e32 v6, v2
	v_mov_b32_e32 v7, v2
	v_mov_b32_e32 v8, v2
	v_mov_b32_e32 v9, v2
	v_mov_b32_e32 v10, v2
	v_mov_b32_e32 v11, v2
	v_mov_b32_e32 v12, v2
	v_mov_b32_e32 v13, v2
	v_mov_b32_e32 v14, v2
	v_mov_b32_e32 v15, v2
	v_mov_b32_e32 v16, v2
	v_mov_b32_e32 v17, v2
	v_mov_b32_e32 v18, v2
	v_mov_b32_e32 v19, v2
	v_mov_b32_e32 v20, v2
	v_mov_b32_e32 v21, v2
	v_mov_b32_e32 v22, v2
	v_mov_b32_e32 v23, v2
	v_mov_b32_e32 v24, v2
	v_mov_b32_e32 v25, v2
	v_mov_b32_e32 v26, v2
	v_mov_b32_e32 v27, v2
	v_mov_b32_e32 v28, v2
	v_mov_b32_e32 v29, v2
	v_mov_b32_e32 v30, v2
	v_mov_b32_e32 v31, v2
	v_mov_b32_e32 v32, v2
	v_mov_b32_e32 v33, v2
	v_mov_b32_e32 v34, v2
	v_mov_b32_e32 v35, v2
	v_mov_b32_e32 v36, v2
	v_mov_b32_e32 v37, v2
	v_mov_b32_e32 v38, v2
	v_mov_b32_e32 v39, v2
; #define MFMA(a, b, c) __builtin_amdgcn_mfma_f32_32x32x16_bf16((a), (b), (c), 0, 0, 0)
; template <int MI, int NI>
; __device__ __forceinline__ void gemm_kloop(const bf16* __restrict__ A, size_t lda, const bf16* __restrict__ Bt, size_t ldb, int K,
;                                            f16v (&acc)[MI][NI], bf16* sA, bf16* sB) {
;     ...
;   for (int kt = 0; kt < KT; ++kt) {
;     __syncthreads();
; #pragma unroll
;     for (int i = 0; i < 2 * MI; ++i) *(u4v*)(sA + (lrow + 32 * i) * 72 + lseg * 8) = ra[i];
; #pragma unroll
;     for (int i = 0; i < 2 * NI; ++i) *(u4v*)(sB + (lrow + 32 * i) * 72 + lseg * 8) = rb[i];
;     __syncthreads();
;     if (kt + 3 < KT) {
;       const int k2 = (kt + 3) << 6;
;       if (tid < 64 * MI) pfs ^= *(const unsigned*)(A + (size_t)tid * lda + k2);
;       if (tid < 64 * NI) pfs ^= *(const unsigned*)(Bt + (size_t)tid * ldb + k2);
;     }
;     if (kt + 1 < KT) {
;       const int k0 = (kt + 1) << 6;
; #pragma unroll
;       for (int i = 0; i < 2 * MI; ++i) ra[i] = *(const u4v*)(A + (size_t)(lrow + 32 * i) * lda + k0 + lseg * 8);
; #pragma unroll
;       for (int i = 0; i < 2 * NI; ++i) rb[i] = *(const u4v*)(Bt + (size_t)(lrow + 32 * i) * ldb + k0 + lseg * 8);
;     }
; #pragma unroll
;     for (int ks = 0; ks < 4; ++ks) {
;       s8v a[MI], b[NI];
; #pragma unroll
;       for (int mi = 0; mi < MI; ++mi) a[mi] = *(const s8v*)(sA + (wm * 32 * MI + mi * 32 + r) * 72 + ks * 16 + hh * 8);
; #pragma unroll
;       for (int ni = 0; ni < NI; ++ni) b[ni] = *(const s8v*)(sB + (wn * 32 * NI + ni * 32 + r) * 72 + ks * 16 + hh * 8);
; #pragma unroll
;       for (int mi = 0; mi < MI; ++mi)
; #pragma unroll
;         for (int ni = 0; ni < NI; ++ni) acc[mi][ni] = MFMA(a[mi], b[ni], acc[mi][ni]);
;     }
	v_mov_b32_e32 v40, v2
	v_mov_b32_e32 v41, v2
	v_mov_b32_e32 v42, v2
	v_mov_b32_e32 v43, v2
	v_mov_b32_e32 v44, v2
	v_mov_b32_e32 v45, v2
	v_mov_b32_e32 v46, v2
	v_mov_b32_e32 v47, v2
	v_mov_b32_e32 v48, v2
	v_mov_b32_e32 v49, v2
	v_mov_b32_e32 v50, v2
	v_mov_b32_e32 v51, v2
	v_mov_b32_e32 v52, v2
	v_mov_b32_e32 v53, v2
	v_mov_b32_e32 v54, v2
	v_mov_b32_e32 v55, v2
	v_mov_b32_e32 v56, v2
	v_mov_b32_e32 v57, v2
	v_mov_b32_e32 v58, v2
	v_mov_b32_e32 v59, v2
	v_mov_b32_e32 v60, v2
	v_mov_b32_e32 v61, v2
	v_mov_b32_e32 v62, v2
	v_mov_b32_e32 v63, v2
	v_mov_b32_e32 v64, v2
	v_mov_b32_e32 v65, v2
	v_mov_b32_e32 v66, v2
	v_mov_b32_e32 v67, v2
	v_mov_b32_e32 v68, v2
	v_mov_b32_e32 v69, v2
	v_mov_b32_e32 v70, v2
	v_mov_b32_e32 v71, v2
	v_mov_b32_e32 v72, v2
	v_mov_b32_e32 v73, v2
	v_mov_b32_e32 v74, v2
	v_mov_b32_e32 v75, v2
	v_mov_b32_e32 v76, v2
	v_mov_b32_e32 v77, v2
	v_mov_b32_e32 v78, v2
	v_mov_b32_e32 v79, v2
	v_mov_b32_e32 v80, v2
	v_mov_b32_e32 v81, v2
	v_mov_b32_e32 v82, v2
	v_mov_b32_e32 v83, v2
	v_mov_b32_e32 v84, v2
	v_mov_b32_e32 v85, v2
	v_mov_b32_e32 v86, v2
	v_mov_b32_e32 v87, v2
	v_mov_b32_e32 v88, v2
	v_mov_b32_e32 v89, v2
	v_mov_b32_e32 v90, v2
	v_mov_b32_e32 v91, v2
	v_mov_b32_e32 v92, v2
	v_mov_b32_e32 v93, v2
	v_mov_b32_e32 v94, v2
	v_mov_b32_e32 v95, v2
	v_mov_b32_e32 v96, v2
	v_mov_b32_e32 v97, v2
	v_mov_b32_e32 v98, v2
	v_mov_b32_e32 v99, v2
	v_mov_b32_e32 v100, v2
	v_mov_b32_e32 v101, v2
	v_mov_b32_e32 v102, v2
	v_mov_b32_e32 v103, v2
	v_mov_b32_e32 v104, v2
	v_mov_b32_e32 v105, v2
	v_mov_b32_e32 v106, v2
	v_mov_b32_e32 v107, v2
	v_mov_b32_e32 v108, v2
	v_mov_b32_e32 v109, v2
	v_mov_b32_e32 v110, v2
	v_mov_b32_e32 v111, v2
	v_mov_b32_e32 v112, v2
	v_mov_b32_e32 v113, v2
	v_mov_b32_e32 v114, v2
	v_mov_b32_e32 v115, v2
	v_mov_b32_e32 v116, v2
	v_mov_b32_e32 v117, v2
	v_mov_b32_e32 v118, v2
	v_mov_b32_e32 v119, v2
	v_mov_b32_e32 v120, v2
	v_mov_b32_e32 v121, v2
	v_mov_b32_e32 v122, v2
	v_mov_b32_e32 v123, v2
	v_mov_b32_e32 v124, v2
	v_mov_b32_e32 v125, v2
	v_mov_b32_e32 v126, v2
	v_mov_b32_e32 v127, v2
	v_mov_b32_e32 v128, v2
	v_mov_b32_e32 v129, v2
	v_readlane_b32 s37, v252, 16
	v_readlane_b32 s38, v252, 17
	v_readlane_b32 s39, v252, 18
	v_readlane_b32 s40, v252, 19
	v_readlane_b32 s41, v252, 20
	s_barrier
	s_waitcnt vmcnt(11)
	ds_write_b128 v184, v[130:133]
	s_waitcnt vmcnt(10)
	ds_write_b128 v184, v[138:141] offset:4608
	s_waitcnt vmcnt(9)
	ds_write_b128 v184, v[142:145] offset:9216
	s_waitcnt vmcnt(8)
	ds_write_b128 v184, v[146:149] offset:13824
	s_waitcnt vmcnt(7)
	ds_write_b128 v184, v[150:153] offset:18432
	s_waitcnt vmcnt(6)
	ds_write_b128 v184, v[154:157] offset:23040
	s_waitcnt vmcnt(5)
	ds_write_b128 v184, v[158:161] offset:27648
	s_waitcnt vmcnt(4)
	ds_write_b128 v184, v[162:165] offset:32256
	s_waitcnt vmcnt(0) lgkmcnt(0)
	s_barrier
	ds_read_b128 v[186:189], v182
	ds_read_b128 v[204:207], v166 offset:36864
	ds_read_b128 v[208:211], v166 offset:40960
	ds_read_b128 v[190:193], v182 offset:4608
	ds_read_b128 v[196:199], v182 offset:9216
	ds_read_b128 v[200:203], v0
	ds_read_b128 v[212:215], v182 offset:32
	ds_read_b128 v[244:247], v167 offset:36864
	ds_read_b128 v[248:251], v167 offset:40960
	ds_read_b128 v[216:219], v182 offset:4640
	ds_read_b128 v[232:235], v182 offset:9248
	ds_read_b128 v[236:239], v0 offset:32
	s_waitcnt lgkmcnt(10)
	v_mfma_f32_32x32x16_bf16 v[114:129], v[186:189], v[204:207], v[114:129]
	s_add_u32 m0, s96, 16256
	s_nop 0
	s_waitcnt lgkmcnt(9)
	v_mfma_f32_32x32x16_bf16 v[98:113], v[186:189], v[208:211], v[98:113]
	global_load_lds_dwordx4 v134, s[58:59] offset:128
	ds_read_b128 v[186:189], v182 offset:64
	s_waitcnt lgkmcnt(9)
	v_mfma_f32_32x32x16_bf16 v[82:97], v[190:193], v[204:207], v[82:97]
	global_load_lds_dwordx4 v135, s[58:59] offset:1152
	v_mfma_f32_32x32x16_bf16 v[66:81], v[190:193], v[208:211], v[66:81]
	global_load_lds_dwordx4 v136, s[58:59] offset:2176
	ds_read_b128 v[190:193], v182 offset:4672
	s_waitcnt lgkmcnt(9)
	v_mfma_f32_32x32x16_bf16 v[50:65], v[196:199], v[204:207], v[50:65]
	global_load_lds_dwordx4 v137, s[58:59] offset:3200
	v_mfma_f32_32x32x16_bf16 v[34:49], v[196:199], v[208:211], v[34:49]
	global_load_dwordx4 v[130:133], v178, s[56:57] offset:128
	ds_read_b128 v[196:199], v182 offset:9280
	s_waitcnt lgkmcnt(9)
	v_mfma_f32_32x32x16_bf16 v[18:33], v[200:203], v[204:207], v[18:33]
	global_load_dwordx4 v[138:141], v179, s[56:57] offset:128
	v_mfma_f32_32x32x16_bf16 v[2:17], v[200:203], v[208:211], v[2:17]
	global_load_dwordx4 v[142:145], v180, s[56:57] offset:128
	ds_read_b128 v[200:203], v0 offset:64
	ds_read_b128 v[204:207], v168 offset:36864
	ds_read_b128 v[208:211], v168 offset:40960
	s_waitcnt lgkmcnt(10)
	v_mfma_f32_32x32x16_bf16 v[114:129], v[212:215], v[244:247], v[114:129]
	global_load_dwordx4 v[146:149], v181, s[56:57] offset:128
	s_waitcnt lgkmcnt(9)
	v_mfma_f32_32x32x16_bf16 v[98:113], v[212:215], v[248:251], v[98:113]
	global_load_dwordx4 v[150:153], v185, s[56:57] offset:128
	ds_read_b128 v[212:215], v182 offset:96
	s_waitcnt lgkmcnt(9)
	v_mfma_f32_32x32x16_bf16 v[82:97], v[216:219], v[244:247], v[82:97]
	global_load_dwordx4 v[154:157], v222, s[56:57] offset:128
	v_mfma_f32_32x32x16_bf16 v[66:81], v[216:219], v[248:251], v[66:81]
	global_load_dwordx4 v[158:161], v223, s[56:57] offset:128
	ds_read_b128 v[216:219], v182 offset:4704
	s_waitcnt lgkmcnt(9)
	v_mfma_f32_32x32x16_bf16 v[50:65], v[232:235], v[244:247], v[50:65]
	global_load_dwordx4 v[162:165], v227, s[56:57] offset:128
	v_mfma_f32_32x32x16_bf16 v[34:49], v[232:235], v[248:251], v[34:49]
	ds_read_b128 v[232:235], v182 offset:9312
	s_waitcnt lgkmcnt(9)
; #define MFMA(a, b, c) __builtin_amdgcn_mfma_f32_32x32x16_bf16((a), (b), (c), 0, 0, 0)
; template <int MI, int NI>
; __device__ __forceinline__ void gemm_kloop(const bf16* __restrict__ A, size_t lda, const bf16* __restrict__ Bt, size_t ldb, int K,
;                                            f16v (&acc)[MI][NI], bf16* sA, bf16* sB) {
;     ...
;   for (int kt = 0; kt < KT; ++kt) {
;     __syncthreads();
; #pragma unroll
;     for (int i = 0; i < 2 * MI; ++i) *(u4v*)(sA + (lrow + 32 * i) * 72 + lseg * 8) = ra[i];
; #pragma unroll
;     for (int i = 0; i < 2 * NI; ++i) *(u4v*)(sB + (lrow + 32 * i) * 72 + lseg * 8) = rb[i];
;     __syncthreads();
;     if (kt + 3 < KT) {
;       const int k2 = (kt + 3) << 6;
;       if (tid < 64 * MI) pfs ^= *(const unsigned*)(A + (size_t)tid * lda + k2);
;       if (tid < 64 * NI) pfs ^= *(const unsigned*)(Bt + (size_t)tid * ldb + k2);
;     }
;     if (kt + 1 < KT) {
;       const int k0 = (kt + 1) << 6;
; #pragma unroll
;       for (int i = 0; i < 2 * MI; ++i) ra[i] = *(const u4v*)(A + (size_t)(lrow + 32 * i) * lda + k0 + lseg * 8);
; #pragma unroll
;       for (int i = 0; i < 2 * NI; ++i) rb[i] = *(const u4v*)(Bt + (size_t)(lrow + 32 * i) * ldb + k0 + lseg * 8);
;     }
; #pragma unroll
;     for (int ks = 0; ks < 4; ++ks) {
;       s8v a[MI], b[NI];
; #pragma unroll
;       for (int mi = 0; mi < MI; ++mi) a[mi] = *(const s8v*)(sA + (wm * 32 * MI + mi * 32 + r) * 72 + ks * 16 + hh * 8);
; #pragma unroll
;       for (int ni = 0; ni < NI; ++ni) b[ni] = *(const s8v*)(sB + (wn * 32 * NI + ni * 32 + r) * 72 + ks * 16 + hh * 8);
; #pragma unroll
;       for (int mi = 0; mi < MI; ++mi)
; #pragma unroll
;         for (int ni = 0; ni < NI; ++ni) acc[mi][ni] = MFMA(a[mi], b[ni], acc[mi][ni]);
;     }
	v_mfma_f32_32x32x16_bf16 v[18:33], v[236:239], v[244:247], v[18:33]
	v_mfma_f32_32x32x16_bf16 v[2:17], v[236:239], v[248:251], v[2:17]
	ds_read_b128 v[236:239], v0 offset:96
	ds_read_b128 v[244:247], v169 offset:36864
	ds_read_b128 v[248:251], v169 offset:40960
	s_waitcnt lgkmcnt(7)
	v_mfma_f32_32x32x16_bf16 v[114:129], v[186:189], v[204:207], v[114:129]
	s_waitcnt lgkmcnt(6)
	v_mfma_f32_32x32x16_bf16 v[98:113], v[186:189], v[208:211], v[98:113]
	v_mfma_f32_32x32x16_bf16 v[82:97], v[190:193], v[204:207], v[82:97]
	v_mfma_f32_32x32x16_bf16 v[66:81], v[190:193], v[208:211], v[66:81]
	v_mfma_f32_32x32x16_bf16 v[50:65], v[196:199], v[204:207], v[50:65]
	v_mfma_f32_32x32x16_bf16 v[34:49], v[196:199], v[208:211], v[34:49]
	v_mfma_f32_32x32x16_bf16 v[2:17], v[200:203], v[208:211], v[2:17]
	v_mfma_f32_32x32x16_bf16 v[18:33], v[200:203], v[204:207], v[18:33]
	s_waitcnt lgkmcnt(1)
	v_mfma_f32_32x32x16_bf16 v[114:129], v[212:215], v[244:247], v[114:129]
	s_waitcnt lgkmcnt(0)
	v_mfma_f32_32x32x16_bf16 v[98:113], v[212:215], v[248:251], v[98:113]
	v_mfma_f32_32x32x16_bf16 v[82:97], v[216:219], v[244:247], v[82:97]
	v_mfma_f32_32x32x16_bf16 v[66:81], v[216:219], v[248:251], v[66:81]
	v_mfma_f32_32x32x16_bf16 v[50:65], v[232:235], v[244:247], v[50:65]
	v_mfma_f32_32x32x16_bf16 v[34:49], v[232:235], v[248:251], v[34:49]
	v_mfma_f32_32x32x16_bf16 v[18:33], v[236:239], v[244:247], v[18:33]
	v_mfma_f32_32x32x16_bf16 v[2:17], v[236:239], v[248:251], v[2:17]
	s_add_u32 s56, s56, 0x80
	s_addc_u32 s57, s57, 0
	s_add_u32 s58, s58, 0x80
	s_addc_u32 s59, s59, 0
	s_barrier
	s_waitcnt vmcnt(7)
	ds_write_b128 v184, v[130:133]
	s_waitcnt vmcnt(6)
	ds_write_b128 v184, v[138:141] offset:4608
	s_waitcnt vmcnt(5)
	ds_write_b128 v184, v[142:145] offset:9216
	s_waitcnt vmcnt(4)
	ds_write_b128 v184, v[146:149] offset:13824
	s_waitcnt vmcnt(3)
	ds_write_b128 v184, v[150:153] offset:18432
	s_waitcnt vmcnt(2)
	ds_write_b128 v184, v[154:157] offset:23040
	s_waitcnt vmcnt(1)
	ds_write_b128 v184, v[158:161] offset:27648
	s_waitcnt vmcnt(0)
	ds_write_b128 v184, v[162:165] offset:32256
	s_waitcnt lgkmcnt(0)
	s_barrier
	ds_read_b128 v[186:189], v182
	ds_read_b128 v[204:207], v166 offset:53248
	ds_read_b128 v[208:211], v166 offset:57344
	ds_read_b128 v[190:193], v182 offset:4608
	ds_read_b128 v[196:199], v182 offset:9216
	ds_read_b128 v[200:203], v0
	ds_read_b128 v[212:215], v182 offset:32
	ds_read_b128 v[244:247], v167 offset:53248
	ds_read_b128 v[248:251], v167 offset:57344
	ds_read_b128 v[216:219], v182 offset:4640
	ds_read_b128 v[232:235], v182 offset:9248
	ds_read_b128 v[236:239], v0 offset:32
	s_waitcnt lgkmcnt(10)
	v_mfma_f32_32x32x16_bf16 v[114:129], v[186:189], v[204:207], v[114:129]
	s_add_u32 m0, s96, -128
	s_nop 0
	s_waitcnt lgkmcnt(9)
	v_mfma_f32_32x32x16_bf16 v[98:113], v[186:189], v[208:211], v[98:113]
	global_load_lds_dwordx4 v134, s[58:59] offset:128
	ds_read_b128 v[186:189], v182 offset:64
	s_waitcnt lgkmcnt(9)
	v_mfma_f32_32x32x16_bf16 v[82:97], v[190:193], v[204:207], v[82:97]
	global_load_lds_dwordx4 v135, s[58:59] offset:1152
	v_mfma_f32_32x32x16_bf16 v[66:81], v[190:193], v[208:211], v[66:81]
	global_load_lds_dwordx4 v136, s[58:59] offset:2176
	ds_read_b128 v[190:193], v182 offset:4672
	s_waitcnt lgkmcnt(9)
	v_mfma_f32_32x32x16_bf16 v[50:65], v[196:199], v[204:207], v[50:65]
	global_load_lds_dwordx4 v137, s[58:59] offset:3200
	v_mfma_f32_32x32x16_bf16 v[34:49], v[196:199], v[208:211], v[34:49]
	global_load_dwordx4 v[130:133], v178, s[56:57] offset:128
	ds_read_b128 v[196:199], v182 offset:9280
	s_waitcnt lgkmcnt(9)
	v_mfma_f32_32x32x16_bf16 v[18:33], v[200:203], v[204:207], v[18:33]
	global_load_dwordx4 v[138:141], v179, s[56:57] offset:128
	v_mfma_f32_32x32x16_bf16 v[2:17], v[200:203], v[208:211], v[2:17]
	global_load_dwordx4 v[142:145], v180, s[56:57] offset:128
	ds_read_b128 v[200:203], v0 offset:64
	ds_read_b128 v[204:207], v168 offset:53248
	ds_read_b128 v[208:211], v168 offset:57344
	s_waitcnt lgkmcnt(10)
	v_mfma_f32_32x32x16_bf16 v[114:129], v[212:215], v[244:247], v[114:129]
	global_load_dwordx4 v[146:149], v181, s[56:57] offset:128
	s_waitcnt lgkmcnt(9)
	v_mfma_f32_32x32x16_bf16 v[98:113], v[212:215], v[248:251], v[98:113]
	global_load_dwordx4 v[150:153], v185, s[56:57] offset:128
	ds_read_b128 v[212:215], v182 offset:96
	s_waitcnt lgkmcnt(9)
	v_mfma_f32_32x32x16_bf16 v[82:97], v[216:219], v[244:247], v[82:97]
	global_load_dwordx4 v[154:157], v222, s[56:57] offset:128
	v_mfma_f32_32x32x16_bf16 v[66:81], v[216:219], v[248:251], v[66:81]
	global_load_dwordx4 v[158:161], v223, s[56:57] offset:128
	ds_read_b128 v[216:219], v182 offset:4704
	s_waitcnt lgkmcnt(9)
	v_mfma_f32_32x32x16_bf16 v[50:65], v[232:235], v[244:247], v[50:65]
	global_load_dwordx4 v[162:165], v227, s[56:57] offset:128
	v_mfma_f32_32x32x16_bf16 v[34:49], v[232:235], v[248:251], v[34:49]
	ds_read_b128 v[232:235], v182 offset:9312
	s_waitcnt lgkmcnt(9)
	v_mfma_f32_32x32x16_bf16 v[18:33], v[236:239], v[244:247], v[18:33]
	v_mfma_f32_32x32x16_bf16 v[2:17], v[236:239], v[248:251], v[2:17]
	ds_read_b128 v[236:239], v0 offset:96
	ds_read_b128 v[244:247], v169 offset:53248
	ds_read_b128 v[248:251], v169 offset:57344
	s_waitcnt lgkmcnt(7)
	v_mfma_f32_32x32x16_bf16 v[114:129], v[186:189], v[204:207], v[114:129]
	s_waitcnt lgkmcnt(6)
	v_mfma_f32_32x32x16_bf16 v[98:113], v[186:189], v[208:211], v[98:113]
	v_mfma_f32_32x32x16_bf16 v[82:97], v[190:193], v[204:207], v[82:97]
	v_mfma_f32_32x32x16_bf16 v[66:81], v[190:193], v[208:211], v[66:81]
	v_mfma_f32_32x32x16_bf16 v[50:65], v[196:199], v[204:207], v[50:65]
	v_mfma_f32_32x32x16_bf16 v[34:49], v[196:199], v[208:211], v[34:49]
	v_mfma_f32_32x32x16_bf16 v[2:17], v[200:203], v[208:211], v[2:17]
	v_mfma_f32_32x32x16_bf16 v[18:33], v[200:203], v[204:207], v[18:33]
	s_waitcnt lgkmcnt(1)
	v_mfma_f32_32x32x16_bf16 v[114:129], v[212:215], v[244:247], v[114:129]
	s_waitcnt lgkmcnt(0)
	v_mfma_f32_32x32x16_bf16 v[98:113], v[212:215], v[248:251], v[98:113]
	v_mfma_f32_32x32x16_bf16 v[82:97], v[216:219], v[244:247], v[82:97]
	v_mfma_f32_32x32x16_bf16 v[66:81], v[216:219], v[248:251], v[66:81]
	v_mfma_f32_32x32x16_bf16 v[50:65], v[232:235], v[244:247], v[50:65]
	v_mfma_f32_32x32x16_bf16 v[34:49], v[232:235], v[248:251], v[34:49]
	v_mfma_f32_32x32x16_bf16 v[18:33], v[236:239], v[244:247], v[18:33]
	v_mfma_f32_32x32x16_bf16 v[2:17], v[236:239], v[248:251], v[2:17]
	s_add_u32 s56, s56, 0x80
	s_addc_u32 s57, s57, 0
	s_add_u32 s58, s58, 0x80
	s_addc_u32 s59, s59, 0
	s_movk_i32 s94, 6

; __device__ __forceinline__ int tid_opaque() { int t = threadIdx.x; asm volatile("" : "+v"(t)); return t; }
; #define ZERO_ACC(acc, MI_, NI_)                 \
;   _Pragma("unroll") for (int mi = 0; mi < MI_; ++mi) \
;   _Pragma("unroll") for (int ni = 0; ni < NI_; ++ni) \
;   _Pragma("unroll") for (int e = 0; e < 16; ++e) acc[mi][ni][e] = 0.f;
; template <int MI, int NI>
; __device__ __forceinline__ void gemm_kloop(const bf16* __restrict__ A, size_t lda, const bf16* __restrict__ Bt, size_t ldb, int K,
;                                            f16v (&acc)[MI][NI], bf16* sA, bf16* sB) {
;   const int tid = tid_opaque(), lane = tid & 63, w = tid >> 6;
;   const int r = lane & 31, hh = lane >> 5;
;   const int wm = w >> 1, wn = w & 1;
;   const int lrow = tid >> 3, lseg = tid & 7;
;   u4v ra[2 * MI], rb[2 * NI];
;   const int KT = K >> 6;
; #pragma unroll
;   for (int i = 0; i < 2 * MI; ++i) ra[i] = *(const u4v*)(A + (size_t)(lrow + 32 * i) * lda + lseg * 8);
; #pragma unroll
;   for (int i = 0; i < 2 * NI; ++i) rb[i] = *(const u4v*)(Bt + (size_t)(lrow + 32 * i) * ldb + lseg * 8);
; __device__ __forceinline__ void gemm1_tile(const Params& p, int layer, int mt, int nt, bf16* sA, bf16* sB) {
;   const int m0 = mt * 256;
;   f16v acc[4][2];
;   ZERO_ACC(acc, 4, 2)
;   gemm_kloop<4, 2>(p.h + (size_t)m0 * DM, DM, p.WinT + (size_t)nt * 128 * DM, DM, DM, acc, sA, sB);
.LBB0_1595:
	s_lshr_b32 s0, s28, 4
	s_and_b32 s0, s0, 16
	s_xor_b32 s20, s0, 31
	s_min_u32 s22, s20, 16
	s_lshl_b32 s20, s22, 2
	v_cvt_f32_ubyte0_e32 v0, s20
	v_rcp_iflag_f32_e32 v2, v0
	v_cvt_f32_ubyte0_e32 v3, s28
	s_and_b32 s23, s28, 0xff
	v_readlane_b32 s64, v252, 23
	v_mul_f32_e32 v2, v3, v2
	v_trunc_f32_e32 v2, v2
	v_cvt_u32_f32_e32 v4, v2
	v_fma_f32 v2, -v2, v0, v3
	v_cmp_ge_f32_e64 s[20:21], |v2|, v0
	s_cmp_lg_u64 s[20:21], 0
	v_readfirstlane_b32 s20, v4
	s_addc_u32 s20, s20, 0
	s_and_b32 s20, s20, 0xff
	s_lshl_b32 s20, s20, 2
	s_mul_i32 s22, s22, s20
	s_sub_i32 s21, s23, s22
	s_sext_i32_i16 s22, s21
	s_bfe_u32 s22, s22, 0x2001d
	s_add_i32 s22, s21, s22
	s_sext_i32_i16 s23, s22
	s_and_b32 s22, s22, 0xfffc
	s_sub_i32 s21, s21, s22
	s_add_i32 s20, s20, s88
	s_sext_i32_i16 s21, s21
	s_add_i32 s20, s20, s21
	s_ashr_i32 s21, s23, 2
	s_lshl_b32 s20, s20, 8
	s_add_i32 s22, s0, s21
	s_ashr_i32 s21, s20, 31
	s_lshl_b64 s[24:25], s[20:21], 11
	v_readlane_b32 s66, v252, 25
	v_mov_b32_e32 v18, v195
	v_readlane_b32 s67, v252, 26
	s_add_u32 s26, s66, s24
	s_addc_u32 s27, s67, s25
	v_ashrrev_i32_e32 v2, 3, v18
	v_lshlrev_b32_e32 v0, 4, v18
	v_and_b32_e32 v0, 0x70, v0
	v_ashrrev_i32_e32 v3, 31, v2
	v_lshl_add_u64 v[4:5], s[26:27], 0, v[0:1]
	v_lshlrev_b64 v[6:7], 11, v[2:3]
	s_mov_b64 s[26:27], 0x10000
	v_lshl_add_u64 v[10:11], v[6:7], 0, s[26:27]
	v_lshl_add_u64 v[8:9], v[4:5], 0, v[6:7]
	v_lshl_add_u64 v[12:13], v[4:5], 0, v[10:11]
	s_mov_b64 s[26:27], 0x20000
	global_load_dwordx4 v[130:133], v[8:9], off
	global_load_dwordx4 v[138:141], v[12:13], off
	v_lshl_add_u64 v[12:13], v[6:7], 0, s[26:27]
	s_mov_b64 s[26:27], 0x30000
	v_lshl_add_u64 v[16:17], v[6:7], 0, s[26:27]
	v_lshl_add_u64 v[14:15], v[4:5], 0, v[12:13]
	v_lshl_add_u64 v[4:5], v[4:5], 0, v[16:17]
	global_load_dwordx4 v[142:145], v[14:15], off
	global_load_dwordx4 v[146:149], v[4:5], off
	v_add_co_u32_e32 v4, vcc, s62, v8
	s_mov_b32 s0, 0x50000
	s_nop 0
	v_addc_co_u32_e32 v5, vcc, 0, v9, vcc
	v_add_co_u32_e32 v14, vcc, s0, v8
	s_ashr_i32 s23, s22, 31
	s_nop 0
	v_addc_co_u32_e32 v15, vcc, 0, v9, vcc
	s_lshl_b64 s[30:31], s[22:23], 18
	global_load_dwordx4 v[150:153], v[4:5], off
	global_load_dwordx4 v[154:157], v[14:15], off
	v_add_co_u32_e32 v4, vcc, s92, v8
	s_add_u32 s34, s10, s30
	s_nop 0
	v_addc_co_u32_e32 v5, vcc, 0, v9, vcc
	s_addc_u32 s35, s11, s31
	v_add_co_u32_e32 v8, vcc, s93, v8
	v_and_b32_e32 v3, 0xfffff9f, v18
	s_nop 0
	v_addc_co_u32_e32 v9, vcc, 0, v9, vcc
	global_load_dwordx4 v[158:161], v[4:5], off
	global_load_dwordx4 v[162:165], v[8:9], off
	v_lshl_add_u64 v[4:5], s[34:35], 0, v[0:1]
	v_lshl_add_u64 v[8:9], v[4:5], 0, v[6:7]
	v_lshl_add_u64 v[10:11], v[4:5], 0, v[10:11]
	v_lshl_add_u64 v[8:9], v[4:5], 0, v[12:13]
	v_lshl_add_u64 v[4:5], v[4:5], 0, v[16:17]
	v_mul_lo_u32 v8, v2, s33
	v_or_b32_e32 v2, 0x60, v18
	v_mul_lo_u32 v9, v3, s33
	v_mul_lo_u32 v10, v2, s33
	v_lshl_add_u64 v[2:3], v[6:7], 0, s[24:25]
	v_or_b32_e32 v2, v2, v0
	s_waitcnt vmcnt(31)
	v_lshl_add_u64 v[178:179], s[66:67], 0, v[2:3]
	v_lshl_add_u64 v[2:3], s[30:31], 0, v[6:7]
	v_lshrrev_b32_e32 v4, 1, v18
	v_and_b32_e32 v5, 0x5f, v18
	v_or_b32_e32 v2, v2, v0
	v_and_b32_e32 v4, 16, v4
	v_mul_u32_u24_e32 v5, 0x90, v5
	v_lshl_add_u64 v[180:181], s[10:11], 0, v[2:3]
	v_mov_b32_e32 v2, 0
	s_mov_b64 s[24:25], 0
	s_waitcnt vmcnt(30)
	v_add_u32_e32 v184, v0, v8
	v_add_u32_e32 v182, v4, v9
	v_add_u32_e32 v0, v4, v10
	v_add_u32_e32 v183, v4, v5
	v_readfirstlane_b32 s56, v178
	v_readfirstlane_b32 s57, v179
	v_readfirstlane_b32 s58, v180
	v_readfirstlane_b32 s59, v181
	v_readfirstlane_b32 s94, v195
	v_subrev_u32_e32 v178, s56, v178
	v_add_u32_e32 v179, 0x10000, v178
	v_add_u32_e32 v180, 0x20000, v178
	v_add_u32_e32 v181, 0x30000, v178
	v_add_u32_e32 v185, 0x40000, v178
	v_add_u32_e32 v222, 0x50000, v178
	v_add_u32_e32 v223, 0x60000, v178
	v_add_u32_e32 v227, 0x70000, v178
	s_lshr_b32 s94, s94, 6
	s_mul_i32 s95, s94, 0x4000
	s_sub_u32 s58, s58, s95
	s_subb_u32 s59, s59, 0
	s_lshl_b32 s96, s94, 12
	s_add_u32 s96, s96, 36864
	v_and_b32_e32 v170, 63, v195
	v_lshrrev_b32_e32 v171, 3, v170
	v_lshrrev_b32_e32 v172, 4, v170
	v_and_b32_e32 v173, 7, v170
	v_xor_b32_e32 v172, v172, v173
	v_lshlrev_b32_e32 v172, 4, v172
	v_lshrrev_b32_e32 v173, 6, v195
	v_lshl_add_u32 v170, v173, 5, v171
	v_mul_u32_u24_e32 v170, 0x800, v170
	v_add_u32_e32 v134, v170, v172
	v_xor_b32_e32 v172, 64, v172
	v_add_u32_e32 v170, v170, v172
	v_add_u32_e32 v135, 0x3c00, v170
	v_add_u32_e32 v136, 0x7800, v134
	v_add_u32_e32 v137, 0xb400, v170
	v_and_b32_e32 v170, 31, v195
	v_bfe_u32 v171, v195, 5, 1
	v_bfe_u32 v172, v170, 1, 3
	v_xor_b32_e32 v171, v171, v172
	v_lshlrev_b32_e32 v171, 4, v171
	v_bfe_u32 v172, v195, 6, 1
	v_lshl_add_u32 v172, v172, 6, v170
	v_lshl_add_u32 v166, v172, 7, v171
	v_xor_b32_e32 v167, 32, v166
	v_xor_b32_e32 v168, 64, v166
	v_xor_b32_e32 v169, 96, v166
	s_add_u32 m0, s96, 0
	s_nop 0
	global_load_lds_dwordx4 v134, s[58:59] offset:0
	global_load_lds_dwordx4 v135, s[58:59] offset:1024
	global_load_lds_dwordx4 v136, s[58:59] offset:2048
	global_load_lds_dwordx4 v137, s[58:59] offset:3072
	v_mov_b32_e32 v3, v2
	v_mov_b32_e32 v4, v2
	v_mov_b32_e32 v5, v2
	v_mov_b32_e32 v6, v2
	v_mov_b32_e32 v7, v2
	v_mov_b32_e32 v8, v2
	v_mov_b32_e32 v9, v2
	v_mov_b32_e32 v10, v2
	v_mov_b32_e32 v11, v2
	v_mov_b32_e32 v12, v2
	v_mov_b32_e32 v13, v2
	v_mov_b32_e32 v14, v2
	v_mov_b32_e32 v15, v2
	v_mov_b32_e32 v16, v2
	v_mov_b32_e32 v17, v2
	v_mov_b32_e32 v18, v2
	v_mov_b32_e32 v19, v2
	v_mov_b32_e32 v20, v2
	v_mov_b32_e32 v21, v2
	v_mov_b32_e32 v22, v2
	v_mov_b32_e32 v23, v2
	v_mov_b32_e32 v24, v2
	v_mov_b32_e32 v25, v2
	v_mov_b32_e32 v26, v2
; #define MFMA(a, b, c) __builtin_amdgcn_mfma_f32_32x32x16_bf16((a), (b), (c), 0, 0, 0)
; #define ZERO_ACC(acc, MI_, NI_)                 \
;   _Pragma("unroll") for (int mi = 0; mi < MI_; ++mi) \
;   _Pragma("unroll") for (int ni = 0; ni < NI_; ++ni) \
;   _Pragma("unroll") for (int e = 0; e < 16; ++e) acc[mi][ni][e] = 0.f;
; template <int MI, int NI>
; __device__ __forceinline__ void gemm_kloop(const bf16* __restrict__ A, size_t lda, const bf16* __restrict__ Bt, size_t ldb, int K,
;                                            f16v (&acc)[MI][NI], bf16* sA, bf16* sB) {
;     ...
;   for (int kt = 0; kt < KT; ++kt) {
;     __syncthreads();
; #pragma unroll
;     for (int i = 0; i < 2 * MI; ++i) *(u4v*)(sA + (lrow + 32 * i) * 72 + lseg * 8) = ra[i];
; #pragma unroll
;     for (int i = 0; i < 2 * NI; ++i) *(u4v*)(sB + (lrow + 32 * i) * 72 + lseg * 8) = rb[i];
;     __syncthreads();
;     if (kt + 3 < KT) {
;       const int k2 = (kt + 3) << 6;
;       if (tid < 64 * MI) pfs ^= *(const unsigned*)(A + (size_t)tid * lda + k2);
;       if (tid < 64 * NI) pfs ^= *(const unsigned*)(Bt + (size_t)tid * ldb + k2);
;     }
;     if (kt + 1 < KT) {
;       const int k0 = (kt + 1) << 6;
; #pragma unroll
;       for (int i = 0; i < 2 * MI; ++i) ra[i] = *(const u4v*)(A + (size_t)(lrow + 32 * i) * lda + k0 + lseg * 8);
; #pragma unroll
;       for (int i = 0; i < 2 * NI; ++i) rb[i] = *(const u4v*)(Bt + (size_t)(lrow + 32 * i) * ldb + k0 + lseg * 8);
;     }
; #pragma unroll
;     for (int ks = 0; ks < 4; ++ks) {
;       s8v a[MI], b[NI];
; #pragma unroll
;       for (int mi = 0; mi < MI; ++mi) a[mi] = *(const s8v*)(sA + (wm * 32 * MI + mi * 32 + r) * 72 + ks * 16 + hh * 8);
; #pragma unroll
;       for (int ni = 0; ni < NI; ++ni) b[ni] = *(const s8v*)(sB + (wn * 32 * NI + ni * 32 + r) * 72 + ks * 16 + hh * 8);
; #pragma unroll
;       for (int mi = 0; mi < MI; ++mi)
; #pragma unroll
;         for (int ni = 0; ni < NI; ++ni) acc[mi][ni] = MFMA(a[mi], b[ni], acc[mi][ni]);
;     }
; __device__ __forceinline__ void gemm1_tile(const Params& p, int layer, int mt, int nt, bf16* sA, bf16* sB) {
;   const int m0 = mt * 256;
;   f16v acc[4][2];
;   ZERO_ACC(acc, 4, 2)
	v_mov_b32_e32 v27, v2
	v_mov_b32_e32 v28, v2
	v_mov_b32_e32 v29, v2
	v_mov_b32_e32 v30, v2
	v_mov_b32_e32 v31, v2
	v_mov_b32_e32 v32, v2
	v_mov_b32_e32 v33, v2
	v_mov_b32_e32 v34, v2
	v_mov_b32_e32 v35, v2
	v_mov_b32_e32 v36, v2
	v_mov_b32_e32 v37, v2
	v_mov_b32_e32 v38, v2
	v_mov_b32_e32 v39, v2
	v_mov_b32_e32 v40, v2
	v_mov_b32_e32 v41, v2
	v_mov_b32_e32 v42, v2
	v_mov_b32_e32 v43, v2
	v_mov_b32_e32 v44, v2
	v_mov_b32_e32 v45, v2
	v_mov_b32_e32 v46, v2
	v_mov_b32_e32 v47, v2
	v_mov_b32_e32 v48, v2
	v_mov_b32_e32 v49, v2
	v_mov_b32_e32 v50, v2
	v_mov_b32_e32 v51, v2
	v_mov_b32_e32 v52, v2
	v_mov_b32_e32 v53, v2
	v_mov_b32_e32 v54, v2
	v_mov_b32_e32 v55, v2
	v_mov_b32_e32 v56, v2
	v_mov_b32_e32 v57, v2
	v_mov_b32_e32 v58, v2
	v_mov_b32_e32 v59, v2
	v_mov_b32_e32 v60, v2
	v_mov_b32_e32 v61, v2
	v_mov_b32_e32 v62, v2
	v_mov_b32_e32 v63, v2
	v_mov_b32_e32 v64, v2
	v_mov_b32_e32 v65, v2
	v_mov_b32_e32 v66, v2
	v_mov_b32_e32 v67, v2
	v_mov_b32_e32 v68, v2
	v_mov_b32_e32 v69, v2
	v_mov_b32_e32 v70, v2
	v_mov_b32_e32 v71, v2
	v_mov_b32_e32 v72, v2
	v_mov_b32_e32 v73, v2
	v_mov_b32_e32 v74, v2
	v_mov_b32_e32 v75, v2
	v_mov_b32_e32 v76, v2
	v_mov_b32_e32 v77, v2
	v_mov_b32_e32 v78, v2
	v_mov_b32_e32 v79, v2
	v_mov_b32_e32 v80, v2
	v_mov_b32_e32 v81, v2
	v_mov_b32_e32 v82, v2
	v_mov_b32_e32 v83, v2
	v_mov_b32_e32 v84, v2
	v_mov_b32_e32 v85, v2
	v_mov_b32_e32 v86, v2
	v_mov_b32_e32 v87, v2
	v_mov_b32_e32 v88, v2
	v_mov_b32_e32 v89, v2
	v_mov_b32_e32 v90, v2
	v_mov_b32_e32 v91, v2
	v_mov_b32_e32 v92, v2
	v_mov_b32_e32 v93, v2
	v_mov_b32_e32 v94, v2
	v_mov_b32_e32 v95, v2
	v_mov_b32_e32 v96, v2
	v_mov_b32_e32 v97, v2
	v_mov_b32_e32 v98, v2
	v_mov_b32_e32 v99, v2
	v_mov_b32_e32 v100, v2
	v_mov_b32_e32 v101, v2
	v_mov_b32_e32 v102, v2
	v_mov_b32_e32 v103, v2
	v_mov_b32_e32 v104, v2
	v_mov_b32_e32 v105, v2
	v_mov_b32_e32 v106, v2
	v_mov_b32_e32 v107, v2
	v_mov_b32_e32 v108, v2
	v_mov_b32_e32 v109, v2
	v_mov_b32_e32 v110, v2
	v_mov_b32_e32 v111, v2
	v_mov_b32_e32 v112, v2
	v_mov_b32_e32 v113, v2
	v_mov_b32_e32 v114, v2
	v_mov_b32_e32 v115, v2
	v_mov_b32_e32 v116, v2
	v_mov_b32_e32 v117, v2
	v_mov_b32_e32 v118, v2
	v_mov_b32_e32 v119, v2
	v_mov_b32_e32 v120, v2
	v_mov_b32_e32 v121, v2
	v_mov_b32_e32 v122, v2
	v_mov_b32_e32 v123, v2
	v_mov_b32_e32 v124, v2
	v_mov_b32_e32 v125, v2
	v_mov_b32_e32 v126, v2
	v_mov_b32_e32 v127, v2
	v_mov_b32_e32 v128, v2
	v_mov_b32_e32 v129, v2
	v_readlane_b32 s65, v252, 24
	v_readlane_b32 s68, v252, 27
	v_readlane_b32 s69, v252, 28
	v_readlane_b32 s70, v252, 29
	v_readlane_b32 s71, v252, 30
	v_readlane_b32 s72, v252, 31
	v_readlane_b32 s73, v252, 32
	v_readlane_b32 s74, v252, 33
	v_readlane_b32 s75, v252, 34
	v_readlane_b32 s76, v252, 35
	v_readlane_b32 s77, v252, 36
	v_readlane_b32 s78, v252, 37
	v_readlane_b32 s79, v252, 38
	s_barrier
	s_waitcnt vmcnt(11)
	ds_write_b128 v184, v[130:133]
	s_waitcnt vmcnt(10)
	ds_write_b128 v184, v[138:141] offset:4608
	s_waitcnt vmcnt(9)
	ds_write_b128 v184, v[142:145] offset:9216
	s_waitcnt vmcnt(8)
	ds_write_b128 v184, v[146:149] offset:13824
	s_waitcnt vmcnt(7)
	ds_write_b128 v184, v[150:153] offset:18432
	s_waitcnt vmcnt(6)
	ds_write_b128 v184, v[154:157] offset:23040
	s_waitcnt vmcnt(5)
	ds_write_b128 v184, v[158:161] offset:27648
	s_waitcnt vmcnt(4)
	ds_write_b128 v184, v[162:165] offset:32256
	s_waitcnt vmcnt(0) lgkmcnt(0)
	s_barrier
	ds_read_b128 v[186:189], v182
	ds_read_b128 v[204:207], v166 offset:36864
	ds_read_b128 v[208:211], v166 offset:40960
	ds_read_b128 v[190:193], v182 offset:4608
	ds_read_b128 v[196:199], v182 offset:9216
	ds_read_b128 v[200:203], v0
	ds_read_b128 v[212:215], v182 offset:32
	ds_read_b128 v[244:247], v167 offset:36864
	ds_read_b128 v[248:251], v167 offset:40960
	ds_read_b128 v[216:219], v182 offset:4640
	ds_read_b128 v[232:235], v182 offset:9248
	ds_read_b128 v[236:239], v0 offset:32
	s_waitcnt lgkmcnt(10)
	v_mfma_f32_32x32x16_bf16 v[114:129], v[186:189], v[204:207], v[114:129]
	s_add_u32 m0, s96, 16256
	s_nop 0
	s_waitcnt lgkmcnt(9)
	v_mfma_f32_32x32x16_bf16 v[98:113], v[186:189], v[208:211], v[98:113]
	global_load_lds_dwordx4 v134, s[58:59] offset:128
	ds_read_b128 v[186:189], v182 offset:64
	s_waitcnt lgkmcnt(9)
	v_mfma_f32_32x32x16_bf16 v[82:97], v[190:193], v[204:207], v[82:97]
	global_load_lds_dwordx4 v135, s[58:59] offset:1152
	v_mfma_f32_32x32x16_bf16 v[66:81], v[190:193], v[208:211], v[66:81]
	global_load_lds_dwordx4 v136, s[58:59] offset:2176
	ds_read_b128 v[190:193], v182 offset:4672
	s_waitcnt lgkmcnt(9)
	v_mfma_f32_32x32x16_bf16 v[50:65], v[196:199], v[204:207], v[50:65]
	global_load_lds_dwordx4 v137, s[58:59] offset:3200
	v_mfma_f32_32x32x16_bf16 v[34:49], v[196:199], v[208:211], v[34:49]
	global_load_dwordx4 v[130:133], v178, s[56:57] offset:128
	ds_read_b128 v[196:199], v182 offset:9280
	s_waitcnt lgkmcnt(9)
	v_mfma_f32_32x32x16_bf16 v[18:33], v[200:203], v[204:207], v[18:33]
	global_load_dwordx4 v[138:141], v179, s[56:57] offset:128
	v_mfma_f32_32x32x16_bf16 v[2:17], v[200:203], v[208:211], v[2:17]
	global_load_dwordx4 v[142:145], v180, s[56:57] offset:128
	ds_read_b128 v[200:203], v0 offset:64
	ds_read_b128 v[204:207], v168 offset:36864
	ds_read_b128 v[208:211], v168 offset:40960
	s_waitcnt lgkmcnt(10)
	v_mfma_f32_32x32x16_bf16 v[114:129], v[212:215], v[244:247], v[114:129]
	global_load_dwordx4 v[146:149], v181, s[56:57] offset:128
	s_waitcnt lgkmcnt(9)
	v_mfma_f32_32x32x16_bf16 v[98:113], v[212:215], v[248:251], v[98:113]
	global_load_dwordx4 v[150:153], v185, s[56:57] offset:128
	ds_read_b128 v[212:215], v182 offset:96
	s_waitcnt lgkmcnt(9)
; #define MFMA(a, b, c) __builtin_amdgcn_mfma_f32_32x32x16_bf16((a), (b), (c), 0, 0, 0)
; template <int MI, int NI>
; __device__ __forceinline__ void gemm_kloop(const bf16* __restrict__ A, size_t lda, const bf16* __restrict__ Bt, size_t ldb, int K,
;                                            f16v (&acc)[MI][NI], bf16* sA, bf16* sB) {
;     ...
;   for (int kt = 0; kt < KT; ++kt) {
;     __syncthreads();
; #pragma unroll
;     for (int i = 0; i < 2 * MI; ++i) *(u4v*)(sA + (lrow + 32 * i) * 72 + lseg * 8) = ra[i];
; #pragma unroll
;     for (int i = 0; i < 2 * NI; ++i) *(u4v*)(sB + (lrow + 32 * i) * 72 + lseg * 8) = rb[i];
;     __syncthreads();
;     if (kt + 3 < KT) {
;       const int k2 = (kt + 3) << 6;
;       if (tid < 64 * MI) pfs ^= *(const unsigned*)(A + (size_t)tid * lda + k2);
;       if (tid < 64 * NI) pfs ^= *(const unsigned*)(Bt + (size_t)tid * ldb + k2);
;     }
;     if (kt + 1 < KT) {
;       const int k0 = (kt + 1) << 6;
; #pragma unroll
;       for (int i = 0; i < 2 * MI; ++i) ra[i] = *(const u4v*)(A + (size_t)(lrow + 32 * i) * lda + k0 + lseg * 8);
; #pragma unroll
;       for (int i = 0; i < 2 * NI; ++i) rb[i] = *(const u4v*)(Bt + (size_t)(lrow + 32 * i) * ldb + k0 + lseg * 8);
;     }
; #pragma unroll
;     for (int ks = 0; ks < 4; ++ks) {
;       s8v a[MI], b[NI];
; #pragma unroll
;       for (int mi = 0; mi < MI; ++mi) a[mi] = *(const s8v*)(sA + (wm * 32 * MI + mi * 32 + r) * 72 + ks * 16 + hh * 8);
; #pragma unroll
;       for (int ni = 0; ni < NI; ++ni) b[ni] = *(const s8v*)(sB + (wn * 32 * NI + ni * 32 + r) * 72 + ks * 16 + hh * 8);
; #pragma unroll
;       for (int mi = 0; mi < MI; ++mi)
; #pragma unroll
;         for (int ni = 0; ni < NI; ++ni) acc[mi][ni] = MFMA(a[mi], b[ni], acc[mi][ni]);
;     }
	v_mfma_f32_32x32x16_bf16 v[82:97], v[216:219], v[244:247], v[82:97]
	global_load_dwordx4 v[154:157], v222, s[56:57] offset:128
	v_mfma_f32_32x32x16_bf16 v[66:81], v[216:219], v[248:251], v[66:81]
	global_load_dwordx4 v[158:161], v223, s[56:57] offset:128
	ds_read_b128 v[216:219], v182 offset:4704
	s_waitcnt lgkmcnt(9)
	v_mfma_f32_32x32x16_bf16 v[50:65], v[232:235], v[244:247], v[50:65]
	global_load_dwordx4 v[162:165], v227, s[56:57] offset:128
	v_mfma_f32_32x32x16_bf16 v[34:49], v[232:235], v[248:251], v[34:49]
	ds_read_b128 v[232:235], v182 offset:9312
	s_waitcnt lgkmcnt(9)
	v_mfma_f32_32x32x16_bf16 v[18:33], v[236:239], v[244:247], v[18:33]
	v_mfma_f32_32x32x16_bf16 v[2:17], v[236:239], v[248:251], v[2:17]
	ds_read_b128 v[236:239], v0 offset:96
	ds_read_b128 v[244:247], v169 offset:36864
	ds_read_b128 v[248:251], v169 offset:40960
	s_waitcnt lgkmcnt(7)
	v_mfma_f32_32x32x16_bf16 v[114:129], v[186:189], v[204:207], v[114:129]
	s_waitcnt lgkmcnt(6)
	v_mfma_f32_32x32x16_bf16 v[98:113], v[186:189], v[208:211], v[98:113]
	v_mfma_f32_32x32x16_bf16 v[82:97], v[190:193], v[204:207], v[82:97]
	v_mfma_f32_32x32x16_bf16 v[66:81], v[190:193], v[208:211], v[66:81]
	v_mfma_f32_32x32x16_bf16 v[50:65], v[196:199], v[204:207], v[50:65]
	v_mfma_f32_32x32x16_bf16 v[34:49], v[196:199], v[208:211], v[34:49]
	v_mfma_f32_32x32x16_bf16 v[2:17], v[200:203], v[208:211], v[2:17]
	v_mfma_f32_32x32x16_bf16 v[18:33], v[200:203], v[204:207], v[18:33]
	s_waitcnt lgkmcnt(1)
	v_mfma_f32_32x32x16_bf16 v[114:129], v[212:215], v[244:247], v[114:129]
	s_waitcnt lgkmcnt(0)
	v_mfma_f32_32x32x16_bf16 v[98:113], v[212:215], v[248:251], v[98:113]
	v_mfma_f32_32x32x16_bf16 v[82:97], v[216:219], v[244:247], v[82:97]
	v_mfma_f32_32x32x16_bf16 v[66:81], v[216:219], v[248:251], v[66:81]
	v_mfma_f32_32x32x16_bf16 v[50:65], v[232:235], v[244:247], v[50:65]
	v_mfma_f32_32x32x16_bf16 v[34:49], v[232:235], v[248:251], v[34:49]
	v_mfma_f32_32x32x16_bf16 v[18:33], v[236:239], v[244:247], v[18:33]
	v_mfma_f32_32x32x16_bf16 v[2:17], v[236:239], v[248:251], v[2:17]
	s_add_u32 s56, s56, 0x80
	s_addc_u32 s57, s57, 0
	s_add_u32 s58, s58, 0x80
	s_addc_u32 s59, s59, 0
	s_barrier
	s_waitcnt vmcnt(7)
	ds_write_b128 v184, v[130:133]
	s_waitcnt vmcnt(6)
	ds_write_b128 v184, v[138:141] offset:4608
	s_waitcnt vmcnt(5)
	ds_write_b128 v184, v[142:145] offset:9216
	s_waitcnt vmcnt(4)
	ds_write_b128 v184, v[146:149] offset:13824
	s_waitcnt vmcnt(3)
	ds_write_b128 v184, v[150:153] offset:18432
	s_waitcnt vmcnt(2)
	ds_write_b128 v184, v[154:157] offset:23040
	s_waitcnt vmcnt(1)
	ds_write_b128 v184, v[158:161] offset:27648
	s_waitcnt vmcnt(0)
	ds_write_b128 v184, v[162:165] offset:32256
	s_waitcnt lgkmcnt(0)
	s_barrier
; #define MFMA(a, b, c) __builtin_amdgcn_mfma_f32_32x32x16_bf16((a), (b), (c), 0, 0, 0)
; template <int MI, int NI>
; __device__ __forceinline__ void gemm_kloop(const bf16* __restrict__ A, size_t lda, const bf16* __restrict__ Bt, size_t ldb, int K,
;                                            f16v (&acc)[MI][NI], bf16* sA, bf16* sB) {
;     ...
;   for (int kt = 0; kt < KT; ++kt) {
;     __syncthreads();
; #pragma unroll
;     for (int i = 0; i < 2 * MI; ++i) *(u4v*)(sA + (lrow + 32 * i) * 72 + lseg * 8) = ra[i];
; #pragma unroll
;     for (int i = 0; i < 2 * NI; ++i) *(u4v*)(sB + (lrow + 32 * i) * 72 + lseg * 8) = rb[i];
;     __syncthreads();
;     if (kt + 3 < KT) {
;       const int k2 = (kt + 3) << 6;
;       if (tid < 64 * MI) pfs ^= *(const unsigned*)(A + (size_t)tid * lda + k2);
;       if (tid < 64 * NI) pfs ^= *(const unsigned*)(Bt + (size_t)tid * ldb + k2);
;     }
;     if (kt + 1 < KT) {
;       const int k0 = (kt + 1) << 6;
; #pragma unroll
;       for (int i = 0; i < 2 * MI; ++i) ra[i] = *(const u4v*)(A + (size_t)(lrow + 32 * i) * lda + k0 + lseg * 8);
; #pragma unroll
;       for (int i = 0; i < 2 * NI; ++i) rb[i] = *(const u4v*)(Bt + (size_t)(lrow + 32 * i) * ldb + k0 + lseg * 8);
;     }
; #pragma unroll
;     for (int ks = 0; ks < 4; ++ks) {
;       s8v a[MI], b[NI];
; #pragma unroll
;       for (int mi = 0; mi < MI; ++mi) a[mi] = *(const s8v*)(sA + (wm * 32 * MI + mi * 32 + r) * 72 + ks * 16 + hh * 8);
; #pragma unroll
;       for (int ni = 0; ni < NI; ++ni) b[ni] = *(const s8v*)(sB + (wn * 32 * NI + ni * 32 + r) * 72 + ks * 16 + hh * 8);
; #pragma unroll
;       for (int mi = 0; mi < MI; ++mi)
; #pragma unroll
;         for (int ni = 0; ni < NI; ++ni) acc[mi][ni] = MFMA(a[mi], b[ni], acc[mi][ni]);
;     }
	ds_read_b128 v[186:189], v182
	ds_read_b128 v[204:207], v166 offset:53248
	ds_read_b128 v[208:211], v166 offset:57344
	ds_read_b128 v[190:193], v182 offset:4608
	ds_read_b128 v[196:199], v182 offset:9216
	ds_read_b128 v[200:203], v0
	ds_read_b128 v[212:215], v182 offset:32
	ds_read_b128 v[244:247], v167 offset:53248
	ds_read_b128 v[248:251], v167 offset:57344
	ds_read_b128 v[216:219], v182 offset:4640
	ds_read_b128 v[232:235], v182 offset:9248
	ds_read_b128 v[236:239], v0 offset:32
	s_waitcnt lgkmcnt(10)
	v_mfma_f32_32x32x16_bf16 v[114:129], v[186:189], v[204:207], v[114:129]
	s_add_u32 m0, s96, -128
	s_nop 0
	s_waitcnt lgkmcnt(9)
	v_mfma_f32_32x32x16_bf16 v[98:113], v[186:189], v[208:211], v[98:113]
	global_load_lds_dwordx4 v134, s[58:59] offset:128
	ds_read_b128 v[186:189], v182 offset:64
	s_waitcnt lgkmcnt(9)
	v_mfma_f32_32x32x16_bf16 v[82:97], v[190:193], v[204:207], v[82:97]
	global_load_lds_dwordx4 v135, s[58:59] offset:1152
	v_mfma_f32_32x32x16_bf16 v[66:81], v[190:193], v[208:211], v[66:81]
	global_load_lds_dwordx4 v136, s[58:59] offset:2176
	ds_read_b128 v[190:193], v182 offset:4672
	s_waitcnt lgkmcnt(9)
	v_mfma_f32_32x32x16_bf16 v[50:65], v[196:199], v[204:207], v[50:65]
	global_load_lds_dwordx4 v137, s[58:59] offset:3200
	v_mfma_f32_32x32x16_bf16 v[34:49], v[196:199], v[208:211], v[34:49]
	global_load_dwordx4 v[130:133], v178, s[56:57] offset:128
	ds_read_b128 v[196:199], v182 offset:9280
	s_waitcnt lgkmcnt(9)
	v_mfma_f32_32x32x16_bf16 v[18:33], v[200:203], v[204:207], v[18:33]
	global_load_dwordx4 v[138:141], v179, s[56:57] offset:128
	v_mfma_f32_32x32x16_bf16 v[2:17], v[200:203], v[208:211], v[2:17]
	global_load_dwordx4 v[142:145], v180, s[56:57] offset:128
	ds_read_b128 v[200:203], v0 offset:64
	ds_read_b128 v[204:207], v168 offset:53248
	ds_read_b128 v[208:211], v168 offset:57344
	s_waitcnt lgkmcnt(10)
	v_mfma_f32_32x32x16_bf16 v[114:129], v[212:215], v[244:247], v[114:129]
	global_load_dwordx4 v[146:149], v181, s[56:57] offset:128
	s_waitcnt lgkmcnt(9)
	v_mfma_f32_32x32x16_bf16 v[98:113], v[212:215], v[248:251], v[98:113]
	global_load_dwordx4 v[150:153], v185, s[56:57] offset:128
	ds_read_b128 v[212:215], v182 offset:96
	s_waitcnt lgkmcnt(9)
	v_mfma_f32_32x32x16_bf16 v[82:97], v[216:219], v[244:247], v[82:97]
	global_load_dwordx4 v[154:157], v222, s[56:57] offset:128
	v_mfma_f32_32x32x16_bf16 v[66:81], v[216:219], v[248:251], v[66:81]
	global_load_dwordx4 v[158:161], v223, s[56:57] offset:128
	ds_read_b128 v[216:219], v182 offset:4704
	s_waitcnt lgkmcnt(9)
	v_mfma_f32_32x32x16_bf16 v[50:65], v[232:235], v[244:247], v[50:65]
	global_load_dwordx4 v[162:165], v227, s[56:57] offset:128
	v_mfma_f32_32x32x16_bf16 v[34:49], v[232:235], v[248:251], v[34:49]
	ds_read_b128 v[232:235], v182 offset:9312
	s_waitcnt lgkmcnt(9)
	v_mfma_f32_32x32x16_bf16 v[18:33], v[236:239], v[244:247], v[18:33]
	v_mfma_f32_32x32x16_bf16 v[2:17], v[236:239], v[248:251], v[2:17]
	ds_read_b128 v[236:239], v0 offset:96
	ds_read_b128 v[244:247], v169 offset:53248
	ds_read_b128 v[248:251], v169 offset:57344
	s_waitcnt lgkmcnt(7)
	v_mfma_f32_32x32x16_bf16 v[114:129], v[186:189], v[204:207], v[114:129]
	s_waitcnt lgkmcnt(6)
	v_mfma_f32_32x32x16_bf16 v[98:113], v[186:189], v[208:211], v[98:113]
	v_mfma_f32_32x32x16_bf16 v[82:97], v[190:193], v[204:207], v[82:97]
	v_mfma_f32_32x32x16_bf16 v[66:81], v[190:193], v[208:211], v[66:81]
	v_mfma_f32_32x32x16_bf16 v[50:65], v[196:199], v[204:207], v[50:65]
	v_mfma_f32_32x32x16_bf16 v[34:49], v[196:199], v[208:211], v[34:49]
	v_mfma_f32_32x32x16_bf16 v[2:17], v[200:203], v[208:211], v[2:17]
	v_mfma_f32_32x32x16_bf16 v[18:33], v[200:203], v[204:207], v[18:33]
	s_waitcnt lgkmcnt(1)
	v_mfma_f32_32x32x16_bf16 v[114:129], v[212:215], v[244:247], v[114:129]
	s_waitcnt lgkmcnt(0)
	v_mfma_f32_32x32x16_bf16 v[98:113], v[212:215], v[248:251], v[98:113]
	v_mfma_f32_32x32x16_bf16 v[82:97], v[216:219], v[244:247], v[82:97]
	v_mfma_f32_32x32x16_bf16 v[66:81], v[216:219], v[248:251], v[66:81]
	v_mfma_f32_32x32x16_bf16 v[50:65], v[232:235], v[244:247], v[50:65]
	v_mfma_f32_32x32x16_bf16 v[34:49], v[232:235], v[248:251], v[34:49]
	v_mfma_f32_32x32x16_bf16 v[18:33], v[236:239], v[244:247], v[18:33]
	v_mfma_f32_32x32x16_bf16 v[2:17], v[236:239], v[248:251], v[2:17]
	s_add_u32 s56, s56, 0x80
	s_addc_u32 s57, s57, 0
	s_add_u32 s58, s58, 0x80
	s_addc_u32 s59, s59, 0
	s_movk_i32 s94, 6
